# GEMM k-loops: MFMAs of a k-step ordered so that consecutive MFMAs change only one operand fragment (Gray walk), waits unchanged
# speedup vs baseline: 1.0053x; 1.0012x over previous
.LBB0_231:
	s_add_i32 s47, s48, 0x8000
	s_and_b32 s27, s48, 0x8000
	s_and_b32 s50, s47, 0x8000
	s_add_i32 s48, s27, 0
	s_add_i32 s27, s50, 0
	s_add_u32 s70, s27, s71
	s_mov_b32 m0, s70
	s_waitcnt vmcnt(0) lgkmcnt(0)
	s_barrier
	global_load_lds_dwordx4 v244, s[96:97]
	s_add_u32 m0, s70, 0x4000
	s_nop 0
	global_load_lds_dwordx4 v245, s[72:73]
	s_add_u32 m0, s70, 0x1000
	s_nop 0
	global_load_lds_dwordx4 v246, s[96:97]
	s_add_u32 m0, s70, 0x5000
	s_nop 0
	global_load_lds_dwordx4 v247, s[72:73]
	s_add_u32 m0, s70, 0x2000
	s_nop 0
	global_load_lds_dwordx4 v248, s[96:97]
	s_add_u32 m0, s70, 0x6000
	s_nop 0
	global_load_lds_dwordx4 v249, s[72:73]
	s_add_u32 m0, s70, 0x3000
	s_nop 0
	global_load_lds_dwordx4 v250, s[96:97]
	s_add_u32 m0, s70, 0x7000
	s_nop 0
	global_load_lds_dwordx4 v251, s[72:73]
	s_add_u32 s96, s96, 0x80
	s_addc_u32 s97, s97, 0
	s_add_u32 s72, s72, 0x80
	s_addc_u32 s73, s73, 0
	v_add3_u32 v145, s48, v86, v87
	v_add3_u32 v208, s48, v87, v88
	v_add3_u32 v209, s48, v86, v89
	v_add3_u32 v210, s48, v88, v89
	ds_read_b128 v[104:107], v208
	ds_read_b128 v[100:103], v145 offset:16384
	ds_read_b128 v[108:111], v145 offset:18432
	ds_read_b128 v[164:167], v208 offset:2048
	ds_read_b128 v[112:115], v145 offset:20480
	ds_read_b128 v[116:119], v145 offset:22528
	ds_read_b128 v[120:123], v145 offset:24576
	ds_read_b128 v[124:127], v145 offset:26624
	ds_read_b128 v[128:131], v145 offset:28672
	ds_read_b128 v[132:135], v145 offset:30720
	ds_read_b128 v[200:203], v210
	ds_read_b128 v[168:171], v209 offset:16384
	ds_read_b128 v[172:175], v209 offset:18432
	ds_read_b128 v[204:207], v210 offset:2048
	ds_read_b128 v[176:179], v209 offset:20480
	ds_read_b128 v[180:183], v209 offset:22528
	ds_read_b128 v[184:187], v209 offset:24576
	ds_read_b128 v[188:191], v209 offset:26624
	ds_read_b128 v[192:195], v209 offset:28672
	ds_read_b128 v[196:199], v209 offset:30720
	s_add_u32 s24, s24, 0x80
	s_addc_u32 s25, s25, 0
	s_cmpk_eq_i32 s24, 0x780
	s_mov_b32 s48, s47
	s_waitcnt lgkmcnt(15)
	v_mfma_f32_16x16x32_bf16 v[60:63], v[100:103], v[104:107], v[60:63]
	v_mfma_f32_16x16x32_bf16 v[56:59], v[108:111], v[104:107], v[56:59]
	v_mfma_f32_16x16x32_bf16 v[24:27], v[100:103], v[164:167], v[24:27]
	v_mfma_f32_16x16x32_bf16 v[20:23], v[108:111], v[164:167], v[20:23]
	v_mfma_f32_16x16x32_bf16 v[16:19], v[112:115], v[164:167], v[16:19]
	v_mfma_f32_16x16x32_bf16 v[52:55], v[112:115], v[104:107], v[52:55]
	s_waitcnt lgkmcnt(14)
	v_mfma_f32_16x16x32_bf16 v[48:51], v[116:119], v[104:107], v[48:51]
	v_mfma_f32_16x16x32_bf16 v[12:15], v[116:119], v[164:167], v[12:15]
	s_waitcnt lgkmcnt(13)
	v_mfma_f32_16x16x32_bf16 v[8:11], v[120:123], v[164:167], v[8:11]
	v_mfma_f32_16x16x32_bf16 v[44:47], v[120:123], v[104:107], v[44:47]
	s_waitcnt lgkmcnt(12)
	v_mfma_f32_16x16x32_bf16 v[40:43], v[124:127], v[104:107], v[40:43]
	v_mfma_f32_16x16x32_bf16 v[4:7], v[124:127], v[164:167], v[4:7]
	s_waitcnt lgkmcnt(11)
	v_mfma_f32_16x16x32_bf16 v[0:3], v[128:131], v[164:167], v[0:3]
	v_mfma_f32_16x16x32_bf16 v[36:39], v[128:131], v[104:107], v[36:39]
	s_waitcnt lgkmcnt(10)
	v_mfma_f32_16x16x32_bf16 v[32:35], v[132:135], v[104:107], v[32:35]
	v_mfma_f32_16x16x32_bf16 v[28:31], v[132:135], v[164:167], v[28:31]
	s_waitcnt lgkmcnt(8)
	v_mfma_f32_16x16x32_bf16 v[60:63], v[168:171], v[200:203], v[60:63]
	s_waitcnt lgkmcnt(7)
	v_mfma_f32_16x16x32_bf16 v[56:59], v[172:175], v[200:203], v[56:59]
	s_waitcnt lgkmcnt(6)
	v_mfma_f32_16x16x32_bf16 v[24:27], v[168:171], v[204:207], v[24:27]
	v_mfma_f32_16x16x32_bf16 v[20:23], v[172:175], v[204:207], v[20:23]
	s_waitcnt lgkmcnt(5)
	v_mfma_f32_16x16x32_bf16 v[16:19], v[176:179], v[204:207], v[16:19]
	v_mfma_f32_16x16x32_bf16 v[52:55], v[176:179], v[200:203], v[52:55]
	s_waitcnt lgkmcnt(4)
	v_mfma_f32_16x16x32_bf16 v[48:51], v[180:183], v[200:203], v[48:51]
	v_mfma_f32_16x16x32_bf16 v[12:15], v[180:183], v[204:207], v[12:15]
	s_waitcnt lgkmcnt(3)
	v_mfma_f32_16x16x32_bf16 v[8:11], v[184:187], v[204:207], v[8:11]
	v_mfma_f32_16x16x32_bf16 v[44:47], v[184:187], v[200:203], v[44:47]
	s_waitcnt lgkmcnt(2)
	v_mfma_f32_16x16x32_bf16 v[40:43], v[188:191], v[200:203], v[40:43]
	v_mfma_f32_16x16x32_bf16 v[4:7], v[188:191], v[204:207], v[4:7]
	s_waitcnt lgkmcnt(1)
	v_mfma_f32_16x16x32_bf16 v[0:3], v[192:195], v[204:207], v[0:3]
	v_mfma_f32_16x16x32_bf16 v[36:39], v[192:195], v[200:203], v[36:39]
	s_waitcnt lgkmcnt(0)
	v_mfma_f32_16x16x32_bf16 v[32:35], v[196:199], v[200:203], v[32:35]
	v_mfma_f32_16x16x32_bf16 v[28:31], v[196:199], v[204:207], v[28:31]
	s_cbranch_scc0 .LBB0_231
	v_add_u32_e32 v64, s27, v86
	v_add_u32_e32 v136, v64, v87
	v_add3_u32 v108, s27, v87, v88
	s_waitcnt vmcnt(0)
	s_barrier
	ds_read_b128 v[80:83], v136 offset:16384
	ds_read_b128 v[100:103], v136 offset:18432
	ds_read_b128 v[104:107], v108
	ds_read_b128 v[108:111], v108 offset:2048
	ds_read_b128 v[112:115], v136 offset:20480
	ds_read_b128 v[116:119], v136 offset:22528
	ds_read_b128 v[128:131], v136 offset:28672
	s_waitcnt lgkmcnt(2)
	v_mfma_f32_16x16x32_bf16 v[120:123], v[112:115], v[104:107], v[52:55]
	s_nop 2
	ds_read_b128 v[52:55], v136 offset:24576
	ds_read_b128 v[124:127], v136 offset:26624
	s_cmp_gt_i32 s26, 11
	s_waitcnt lgkmcnt(0)
	v_mfma_f32_16x16x32_bf16 v[132:135], v[124:127], v[104:107], v[40:43]
	s_nop 2
	ds_read_b128 v[40:43], v136 offset:30720
	s_cselect_b64 s[24:25], -1, 0
	s_cmp_lt_i32 s26, 12
	v_mfma_f32_16x16x32_bf16 v[60:63], v[80:83], v[104:107], v[60:63]
	s_cselect_b64 s[48:49], -1, 0
	v_mfma_f32_16x16x32_bf16 v[56:59], v[100:103], v[104:107], v[56:59]
	v_mfma_f32_16x16x32_bf16 v[48:51], v[116:119], v[104:107], v[48:51]
	v_mfma_f32_16x16x32_bf16 v[44:47], v[52:55], v[104:107], v[44:47]
	v_mfma_f32_16x16x32_bf16 v[136:139], v[128:131], v[104:107], v[36:39]
	s_waitcnt lgkmcnt(0)
	v_mfma_f32_16x16x32_bf16 v[32:35], v[40:43], v[104:107], v[32:35]
	v_mfma_f32_16x16x32_bf16 v[104:107], v[52:55], v[108:111], v[8:11]
	s_nop 2
	v_add_u32_e32 v8, v64, v89
	v_mfma_f32_16x16x32_bf16 v[24:27], v[80:83], v[108:111], v[24:27]
	v_add3_u32 v9, s27, v89, v88
	v_lshl_or_b32 v64, s26, 7, v90
	s_sub_i32 s26, s26, 18
	v_mfma_f32_16x16x32_bf16 v[80:83], v[112:115], v[108:111], v[16:19]
	s_cmp_lt_u32 s26, 8
	s_cselect_b64 s[26:27], -1, 0
	s_or_b64 s[48:49], s[48:49], s[26:27]
	v_mfma_f32_16x16x32_bf16 v[112:115], v[124:127], v[108:111], v[4:7]
	s_mov_b64 s[26:27], -1
	s_andn2_b64 vcc, exec, s[48:49]
	s_nop 0
	ds_read_b128 v[4:7], v8 offset:16384
	v_mfma_f32_16x16x32_bf16 v[20:23], v[100:103], v[108:111], v[20:23]
	v_mfma_f32_16x16x32_bf16 v[100:103], v[116:119], v[108:111], v[12:15]
	v_mfma_f32_16x16x32_bf16 v[116:119], v[128:131], v[108:111], v[0:3]
	ds_read_b128 v[124:127], v8 offset:18432
	s_nop 1
	ds_read_b128 v[0:3], v9
	ds_read_b128 v[128:131], v9 offset:2048
	ds_read_b128 v[140:143], v8 offset:22528
	ds_read_b128 v[146:149], v8 offset:28672
	s_waitcnt lgkmcnt(3)
	v_mfma_f32_16x16x32_bf16 v[52:55], v[4:7], v[0:3], v[60:63]
	s_nop 2
	ds_read_b128 v[60:63], v8 offset:20480
	v_mfma_f32_16x16x32_bf16 v[108:111], v[40:43], v[108:111], v[28:31]
	s_waitcnt lgkmcnt(0)
	v_mfma_f32_16x16x32_bf16 v[36:39], v[60:63], v[0:3], v[120:123]
	s_nop 2
	ds_read_b128 v[120:123], v8 offset:24576
	v_mfma_f32_16x16x32_bf16 v[40:43], v[140:143], v[0:3], v[48:51]
	s_nop 2
	ds_read_b128 v[48:51], v8 offset:26624
	s_waitcnt lgkmcnt(0)
	v_mfma_f32_16x16x32_bf16 v[16:19], v[48:51], v[0:3], v[132:135]
	s_nop 2
	ds_read_b128 v[132:135], v8 offset:30720
	v_mfma_f32_16x16x32_bf16 v[56:59], v[124:127], v[0:3], v[56:59]
	v_mfma_f32_16x16x32_bf16 v[12:15], v[120:123], v[0:3], v[44:47]
	v_mfma_f32_16x16x32_bf16 v[8:11], v[146:149], v[0:3], v[136:139]
	s_waitcnt lgkmcnt(0)
	v_mfma_f32_16x16x32_bf16 v[0:3], v[132:135], v[0:3], v[32:35]
	v_mfma_f32_16x16x32_bf16 v[28:31], v[4:7], v[128:131], v[24:27]
	v_mfma_f32_16x16x32_bf16 v[20:23], v[124:127], v[128:131], v[20:23]
	v_mfma_f32_16x16x32_bf16 v[4:7], v[60:63], v[128:131], v[80:83]
	v_mfma_f32_16x16x32_bf16 v[24:27], v[140:143], v[128:131], v[100:103]
	s_nop 1
	v_lshl_add_u32 v80, s46, 7, v85
	v_mfma_f32_16x16x32_bf16 v[32:35], v[120:123], v[128:131], v[104:107]
	v_mfma_f32_16x16x32_bf16 v[44:47], v[48:51], v[128:131], v[112:115]
	v_mfma_f32_16x16x32_bf16 v[48:51], v[146:149], v[128:131], v[116:119]
	v_mfma_f32_16x16x32_bf16 v[60:63], v[132:135], v[128:131], v[108:111]
	s_cbranch_vccz .LBB0_240
	s_and_b32 s47, 0xffff, s45
	s_cmp_gt_u32 s47, 17
	s_cbranch_scc0 .LBB0_237
	s_cmp_eq_u32 s47, 26
	s_cselect_b64 s[26:27], -1, 0
	s_and_b64 s[48:49], s[10:11], s[26:27]
	s_and_saveexec_b64 s[26:27], s[48:49]
	s_cbranch_execz .LBB0_236
	global_load_dwordx4 v[100:103], v[72:73], off
	v_mad_i64_i32 v[82:83], s[48:49], v80, s28, v[70:71]
	v_or_b32_e32 v81, 16, v80
	s_waitcnt vmcnt(0)
	v_pk_add_f32 v[102:103], v[54:55], v[102:103]
	v_pk_add_f32 v[100:101], v[52:53], v[100:101]
	global_store_dwordx4 v[82:83], v[100:103], off
	global_load_dwordx4 v[100:103], v[72:73], off offset:16
	v_mad_i64_i32 v[82:83], s[48:49], v80, s28, v[74:75]
	s_waitcnt vmcnt(0)
	v_pk_add_f32 v[102:103], v[58:59], v[102:103]
	v_pk_add_f32 v[100:101], v[56:57], v[100:101]
	global_store_dwordx4 v[82:83], v[100:103], off
	global_load_dwordx4 v[100:103], v[72:73], off
	v_mad_i64_i32 v[82:83], s[48:49], v81, s28, v[70:71]
	s_waitcnt vmcnt(0)
	v_pk_add_f32 v[102:103], v[30:31], v[102:103]
	v_pk_add_f32 v[100:101], v[28:29], v[100:101]
	global_store_dwordx4 v[82:83], v[100:103], off
	global_load_dwordx4 v[100:103], v[72:73], off offset:16
	v_mad_i64_i32 v[82:83], s[48:49], v81, s28, v[74:75]
	s_waitcnt vmcnt(0)
	v_pk_add_f32 v[102:103], v[22:23], v[102:103]
	v_pk_add_f32 v[100:101], v[20:21], v[100:101]
	global_store_dwordx4 v[82:83], v[100:103], off

.LBB0_855:
	s_add_i32 s45, s43, 0x8000
	s_and_b32 s44, s45, 0x8000
	s_add_i32 s44, s44, 0
	s_add_u32 s86, s44, s87
	s_mov_b32 m0, s86
	s_waitcnt vmcnt(0) lgkmcnt(0)
	s_barrier
	global_load_lds_dwordx4 v244, s[96:97]
	s_add_u32 m0, s86, 0x4000
	s_nop 0
	global_load_lds_dwordx4 v245, s[88:89]
	s_add_u32 m0, s86, 0x1000
	s_nop 0
	global_load_lds_dwordx4 v246, s[96:97]
	s_add_u32 m0, s86, 0x5000
	s_nop 0
	global_load_lds_dwordx4 v247, s[88:89]
	s_add_u32 m0, s86, 0x2000
	s_nop 0
	global_load_lds_dwordx4 v248, s[96:97]
	s_add_u32 m0, s86, 0x6000
	s_nop 0
	global_load_lds_dwordx4 v249, s[88:89]
	s_add_u32 m0, s86, 0x3000
	s_nop 0
	global_load_lds_dwordx4 v250, s[96:97]
	s_add_u32 m0, s86, 0x7000
	s_nop 0
	global_load_lds_dwordx4 v251, s[88:89]
	s_add_u32 s96, s96, 0x80
	s_addc_u32 s97, s97, 0
	s_add_u32 s88, s88, 0x80
	s_addc_u32 s89, s89, 0
	s_and_b32 s43, s43, 0x8000
	s_add_i32 s43, s43, 0
	v_add3_u32 v212, s43, v88, v89
	v_add3_u32 v213, s43, v89, v90
	v_add3_u32 v214, s43, v88, v91
	v_add3_u32 v215, s43, v90, v91
	ds_read_b128 v[106:109], v213
	ds_read_b128 v[76:79], v212 offset:16384
	ds_read_b128 v[102:105], v212 offset:18432
	ds_read_b128 v[110:113], v213 offset:2048
	ds_read_b128 v[114:117], v212 offset:20480
	ds_read_b128 v[118:121], v212 offset:22528
	ds_read_b128 v[122:125], v212 offset:24576
	ds_read_b128 v[126:129], v212 offset:26624
	ds_read_b128 v[130:133], v212 offset:28672
	ds_read_b128 v[134:137], v212 offset:30720
	ds_read_b128 v[180:183], v215
	ds_read_b128 v[172:175], v214 offset:16384
	ds_read_b128 v[176:179], v214 offset:18432
	ds_read_b128 v[184:187], v215 offset:2048
	ds_read_b128 v[188:191], v214 offset:20480
	ds_read_b128 v[192:195], v214 offset:22528
	ds_read_b128 v[196:199], v214 offset:24576
	ds_read_b128 v[200:203], v214 offset:26624
	ds_read_b128 v[204:207], v214 offset:28672
	ds_read_b128 v[208:211], v214 offset:30720
	s_add_u32 s34, s34, 0x80
	s_addc_u32 s35, s35, 0
	s_cmpk_eq_i32 s34, 0x780
	s_mov_b32 s43, s45
	s_waitcnt lgkmcnt(15)
	v_mfma_f32_16x16x32_bf16 v[60:63], v[76:79], v[106:109], v[60:63]
	v_mfma_f32_16x16x32_bf16 v[56:59], v[102:105], v[106:109], v[56:59]
	v_mfma_f32_16x16x32_bf16 v[24:27], v[76:79], v[110:113], v[24:27]
	v_mfma_f32_16x16x32_bf16 v[20:23], v[102:105], v[110:113], v[20:23]
	v_mfma_f32_16x16x32_bf16 v[16:19], v[114:117], v[110:113], v[16:19]
	v_mfma_f32_16x16x32_bf16 v[52:55], v[114:117], v[106:109], v[52:55]
	s_waitcnt lgkmcnt(14)
	v_mfma_f32_16x16x32_bf16 v[48:51], v[118:121], v[106:109], v[48:51]
	v_mfma_f32_16x16x32_bf16 v[12:15], v[118:121], v[110:113], v[12:15]
	s_waitcnt lgkmcnt(13)
	v_mfma_f32_16x16x32_bf16 v[8:11], v[122:125], v[110:113], v[8:11]
	v_mfma_f32_16x16x32_bf16 v[44:47], v[122:125], v[106:109], v[44:47]
	s_waitcnt lgkmcnt(12)
	v_mfma_f32_16x16x32_bf16 v[40:43], v[126:129], v[106:109], v[40:43]
	v_mfma_f32_16x16x32_bf16 v[4:7], v[126:129], v[110:113], v[4:7]
	s_waitcnt lgkmcnt(11)
	v_mfma_f32_16x16x32_bf16 v[0:3], v[130:133], v[110:113], v[0:3]
	v_mfma_f32_16x16x32_bf16 v[32:35], v[130:133], v[106:109], v[32:35]
	s_waitcnt lgkmcnt(10)
	v_mfma_f32_16x16x32_bf16 v[28:31], v[134:137], v[106:109], v[28:31]
	v_mfma_f32_16x16x32_bf16 v[36:39], v[134:137], v[110:113], v[36:39]
	s_waitcnt lgkmcnt(8)
	v_mfma_f32_16x16x32_bf16 v[60:63], v[172:175], v[180:183], v[60:63]
	s_waitcnt lgkmcnt(7)
	v_mfma_f32_16x16x32_bf16 v[56:59], v[176:179], v[180:183], v[56:59]
	s_waitcnt lgkmcnt(6)
	v_mfma_f32_16x16x32_bf16 v[24:27], v[172:175], v[184:187], v[24:27]
	v_mfma_f32_16x16x32_bf16 v[20:23], v[176:179], v[184:187], v[20:23]
	s_waitcnt lgkmcnt(5)
	v_mfma_f32_16x16x32_bf16 v[16:19], v[188:191], v[184:187], v[16:19]
	v_mfma_f32_16x16x32_bf16 v[52:55], v[188:191], v[180:183], v[52:55]
	s_waitcnt lgkmcnt(4)
	v_mfma_f32_16x16x32_bf16 v[48:51], v[192:195], v[180:183], v[48:51]
	v_mfma_f32_16x16x32_bf16 v[12:15], v[192:195], v[184:187], v[12:15]
	s_waitcnt lgkmcnt(3)
	v_mfma_f32_16x16x32_bf16 v[8:11], v[196:199], v[184:187], v[8:11]
	v_mfma_f32_16x16x32_bf16 v[44:47], v[196:199], v[180:183], v[44:47]
	s_waitcnt lgkmcnt(2)
	v_mfma_f32_16x16x32_bf16 v[40:43], v[200:203], v[180:183], v[40:43]
	v_mfma_f32_16x16x32_bf16 v[4:7], v[200:203], v[184:187], v[4:7]
	s_waitcnt lgkmcnt(1)
	v_mfma_f32_16x16x32_bf16 v[0:3], v[204:207], v[184:187], v[0:3]
	v_mfma_f32_16x16x32_bf16 v[32:35], v[204:207], v[180:183], v[32:35]
	s_waitcnt lgkmcnt(0)
	v_mfma_f32_16x16x32_bf16 v[28:31], v[208:211], v[180:183], v[28:31]
	v_mfma_f32_16x16x32_bf16 v[36:39], v[208:211], v[184:187], v[36:39]
	s_cbranch_scc0 .LBB0_855
	v_add_u32_e32 v80, s44, v88
	v_add_u32_e32 v81, v80, v89
	v_add3_u32 v106, s44, v89, v90
	s_waitcnt vmcnt(0)
	s_barrier
	ds_read_b128 v[72:75], v81 offset:16384
	ds_read_b128 v[76:79], v81 offset:18432
	ds_read_b128 v[102:105], v106
	ds_read_b128 v[106:109], v106 offset:2048
	ds_read_b128 v[110:113], v81 offset:20480
	ds_read_b128 v[114:117], v81 offset:22528
	ds_read_b128 v[118:121], v81 offset:24576
	ds_read_b128 v[122:125], v81 offset:26624
	ds_read_b128 v[126:129], v81 offset:28672
	ds_read_b128 v[130:133], v81 offset:30720
	v_add_u32_e32 v80, v80, v91
	s_waitcnt lgkmcnt(7)
	v_mfma_f32_16x16x32_bf16 v[60:63], v[72:75], v[102:105], v[60:63]
	s_lshl_b32 s42, s42, 7
	v_mfma_f32_16x16x32_bf16 v[56:59], v[76:79], v[102:105], v[56:59]
	s_waitcnt lgkmcnt(4)
	v_mfma_f32_16x16x32_bf16 v[48:51], v[114:117], v[102:105], v[48:51]
	s_waitcnt lgkmcnt(3)
	v_mfma_f32_16x16x32_bf16 v[44:47], v[118:121], v[102:105], v[44:47]
	s_waitcnt lgkmcnt(2)
	v_mfma_f32_16x16x32_bf16 v[40:43], v[122:125], v[102:105], v[40:43]
	s_waitcnt lgkmcnt(1)
	v_mfma_f32_16x16x32_bf16 v[32:35], v[126:129], v[102:105], v[32:35]
	s_waitcnt lgkmcnt(0)
	v_mfma_f32_16x16x32_bf16 v[28:31], v[130:133], v[102:105], v[28:31]
	v_mfma_f32_16x16x32_bf16 v[24:27], v[72:75], v[106:109], v[24:27]
	ds_read_b128 v[72:75], v80 offset:16384
	v_mfma_f32_16x16x32_bf16 v[52:55], v[110:113], v[102:105], v[52:55]
	v_mfma_f32_16x16x32_bf16 v[20:23], v[76:79], v[106:109], v[20:23]
	v_mfma_f32_16x16x32_bf16 v[16:19], v[110:113], v[106:109], v[16:19]
	v_mfma_f32_16x16x32_bf16 v[12:15], v[114:117], v[106:109], v[12:15]
	v_mfma_f32_16x16x32_bf16 v[8:11], v[118:121], v[106:109], v[8:11]
	v_mfma_f32_16x16x32_bf16 v[4:7], v[122:125], v[106:109], v[4:7]
	v_mfma_f32_16x16x32_bf16 v[0:3], v[126:129], v[106:109], v[0:3]
	v_mfma_f32_16x16x32_bf16 v[102:105], v[130:133], v[106:109], v[36:39]
	s_nop 2
	v_add3_u32 v36, s44, v91, v90
	ds_read_b128 v[76:79], v80 offset:18432
	ds_read_b128 v[106:109], v36
	ds_read_b128 v[110:113], v36 offset:2048
	ds_read_b128 v[130:133], v80 offset:28672
	ds_read_b128 v[134:137], v80 offset:30720
	ds_read_b128 v[114:117], v80 offset:20480
	ds_read_b128 v[118:121], v80 offset:22528
	ds_read_b128 v[122:125], v80 offset:24576
	ds_read_b128 v[126:129], v80 offset:26624
	s_waitcnt lgkmcnt(7)
	v_mfma_f32_16x16x32_bf16 v[60:63], v[72:75], v[106:109], v[60:63]
	v_readlane_b32 s44, v252, 5
	v_readlane_b32 s48, v252, 9
	v_readlane_b32 s49, v252, 10
	s_waitcnt lgkmcnt(5)
	v_mfma_f32_16x16x32_bf16 v[36:39], v[130:133], v[106:109], v[32:35]
	v_readlane_b32 s45, v252, 6
	v_readlane_b32 s46, v252, 7
	v_readlane_b32 s47, v252, 8
	s_waitcnt lgkmcnt(4)
	v_mfma_f32_16x16x32_bf16 v[32:35], v[134:137], v[106:109], v[28:31]
	v_readlane_b32 s50, v252, 11
	v_readlane_b32 s51, v252, 12
	v_readlane_b32 s52, v252, 13
	v_mfma_f32_16x16x32_bf16 v[28:31], v[72:75], v[110:113], v[24:27]
	v_add_u32_e32 v72, s42, v82
	v_mul_hi_i32 v73, v72, s36
	v_lshrrev_b32_e32 v74, 31, v73
	v_mfma_f32_16x16x32_bf16 v[24:27], v[76:79], v[110:113], v[20:23]
	v_readlane_b32 s53, v252, 14
	v_readlane_b32 s54, v252, 15
	v_readlane_b32 s55, v252, 16
	s_waitcnt lgkmcnt(3)
	v_mfma_f32_16x16x32_bf16 v[20:23], v[114:117], v[110:113], v[16:19]
	v_readlane_b32 s56, v252, 17
	v_readlane_b32 s57, v252, 18
	v_readlane_b32 s58, v252, 19
	s_waitcnt lgkmcnt(2)
	v_mfma_f32_16x16x32_bf16 v[16:19], v[118:121], v[110:113], v[12:15]
	v_readlane_b32 s59, v252, 20
	s_waitcnt lgkmcnt(1)
	v_mfma_f32_16x16x32_bf16 v[12:15], v[122:125], v[110:113], v[8:11]
	s_waitcnt lgkmcnt(0)
	v_mfma_f32_16x16x32_bf16 v[8:11], v[126:129], v[110:113], v[4:7]
	s_nop 2
	v_ashrrev_i32_e32 v4, 11, v73
	v_mfma_f32_16x16x32_bf16 v[56:59], v[76:79], v[106:109], v[56:59]
	v_add_u32_e32 v73, v4, v74
	v_mad_i32_i24 v75, v73, s37, v72
	v_lshlrev_b32_e32 v78, 13, v73
	v_mfma_f32_16x16x32_bf16 v[52:55], v[114:117], v[106:109], v[52:55]
	v_cmp_lt_i32_e32 vcc, s38, v75
	v_mov_b64_e32 v[76:77], s[48:49]
	v_add3_u32 v74, v78, v75, s39
	v_mfma_f32_16x16x32_bf16 v[48:51], v[118:121], v[106:109], v[48:51]
	v_mfma_f32_16x16x32_bf16 v[44:47], v[122:125], v[106:109], v[44:47]
	v_mfma_f32_16x16x32_bf16 v[40:43], v[126:129], v[106:109], v[40:43]
	v_mfma_f32_16x16x32_bf16 v[0:3], v[130:133], v[110:113], v[0:3]
	v_mfma_f32_16x16x32_bf16 v[4:7], v[134:137], v[110:113], v[102:105]
	s_and_saveexec_b64 s[34:35], vcc
	s_xor_b64 s[34:35], exec, s[34:35]
	s_cbranch_execz .LBB0_858
	v_readlane_b32 s44, v252, 5
	v_readlane_b32 s45, v252, 6
	v_add3_u32 v72, v78, v75, s39
	v_readlane_b32 s46, v252, 7
	v_readlane_b32 s47, v252, 8
	v_readlane_b32 s48, v252, 9
	v_readlane_b32 s49, v252, 10
	v_readlane_b32 s50, v252, 11
	v_readlane_b32 s51, v252, 12
	v_readlane_b32 s52, v252, 13
	v_readlane_b32 s53, v252, 14
	v_readlane_b32 s54, v252, 15
	v_readlane_b32 s55, v252, 16
	v_readlane_b32 s56, v252, 17
	v_readlane_b32 s57, v252, 18
	v_readlane_b32 s58, v252, 19
	v_readlane_b32 s59, v252, 20
	v_mov_b64_e32 v[76:77], s[44:45]
	s_or_saveexec_b64 s[34:35], s[34:35]
	v_lshl_add_u32 v102, v73, 8, v75
	s_xor_b64 exec, exec, s[34:35]
	s_branch .LBB0_859

.LBB0_1006:
	s_add_i32 s37, s35, 0x8000
	s_and_b32 s36, s37, 0x8000
	s_add_i32 s36, s36, 0
	s_add_u32 s86, s36, s87
	s_mov_b32 m0, s86
	s_waitcnt vmcnt(0) lgkmcnt(0)
	s_barrier
	global_load_lds_dwordx4 v244, s[96:97]
	s_add_u32 m0, s86, 0x4000
	s_nop 0
	global_load_lds_dwordx4 v245, s[88:89]
	s_add_u32 m0, s86, 0x1000
	s_nop 0
	global_load_lds_dwordx4 v246, s[96:97]
	s_add_u32 m0, s86, 0x5000
	s_nop 0
	global_load_lds_dwordx4 v247, s[88:89]
	s_add_u32 m0, s86, 0x2000
	s_nop 0
	global_load_lds_dwordx4 v248, s[96:97]
	s_add_u32 m0, s86, 0x6000
	s_nop 0
	global_load_lds_dwordx4 v249, s[88:89]
	s_add_u32 m0, s86, 0x3000
	s_nop 0
	global_load_lds_dwordx4 v250, s[96:97]
	s_add_u32 m0, s86, 0x7000
	s_nop 0
	global_load_lds_dwordx4 v251, s[88:89]
	s_add_u32 s96, s96, 0x80
	s_addc_u32 s97, s97, 0
	s_add_u32 s88, s88, 0x80
	s_addc_u32 s89, s89, 0
	s_and_b32 s35, s35, 0x8000
	s_add_i32 s35, s35, 0
	v_add3_u32 v143, s35, v80, v81
	v_add3_u32 v145, s35, v81, v82
	v_add3_u32 v206, s35, v80, v83
	v_add3_u32 v207, s35, v82, v83
	ds_read_b128 v[102:105], v145
	ds_read_b128 v[94:97], v143 offset:16384
	ds_read_b128 v[98:101], v143 offset:18432
	ds_read_b128 v[106:109], v145 offset:2048
	ds_read_b128 v[110:113], v143 offset:20480
	ds_read_b128 v[114:117], v143 offset:22528
	ds_read_b128 v[118:121], v143 offset:24576
	ds_read_b128 v[122:125], v143 offset:26624
	ds_read_b128 v[126:129], v143 offset:28672
	ds_read_b128 v[130:133], v143 offset:30720
	ds_read_b128 v[174:177], v207
	ds_read_b128 v[166:169], v206 offset:16384
	ds_read_b128 v[170:173], v206 offset:18432
	ds_read_b128 v[178:181], v207 offset:2048
	ds_read_b128 v[182:185], v206 offset:20480
	ds_read_b128 v[186:189], v206 offset:22528
	ds_read_b128 v[190:193], v206 offset:24576
	ds_read_b128 v[194:197], v206 offset:26624
	ds_read_b128 v[198:201], v206 offset:28672
	ds_read_b128 v[202:205], v206 offset:30720
	s_add_u32 s26, s26, 0x80
	s_addc_u32 s27, s27, 0
	s_cmpk_eq_i32 s26, 0x780
	s_mov_b32 s35, s37
	s_waitcnt lgkmcnt(15)
	v_mfma_f32_16x16x32_bf16 v[60:63], v[94:97], v[102:105], v[60:63]
	v_mfma_f32_16x16x32_bf16 v[56:59], v[98:101], v[102:105], v[56:59]
	v_mfma_f32_16x16x32_bf16 v[28:31], v[94:97], v[106:109], v[28:31]
	v_mfma_f32_16x16x32_bf16 v[24:27], v[98:101], v[106:109], v[24:27]
	v_mfma_f32_16x16x32_bf16 v[16:19], v[110:113], v[106:109], v[16:19]
	v_mfma_f32_16x16x32_bf16 v[52:55], v[110:113], v[102:105], v[52:55]
	s_waitcnt lgkmcnt(14)
	v_mfma_f32_16x16x32_bf16 v[48:51], v[114:117], v[102:105], v[48:51]
	v_mfma_f32_16x16x32_bf16 v[12:15], v[114:117], v[106:109], v[12:15]
	s_waitcnt lgkmcnt(13)
	v_mfma_f32_16x16x32_bf16 v[8:11], v[118:121], v[106:109], v[8:11]
	v_mfma_f32_16x16x32_bf16 v[44:47], v[118:121], v[102:105], v[44:47]
	s_waitcnt lgkmcnt(12)
	v_mfma_f32_16x16x32_bf16 v[40:43], v[122:125], v[102:105], v[40:43]
	v_mfma_f32_16x16x32_bf16 v[4:7], v[122:125], v[106:109], v[4:7]
	s_waitcnt lgkmcnt(11)
	v_mfma_f32_16x16x32_bf16 v[0:3], v[126:129], v[106:109], v[0:3]
	v_mfma_f32_16x16x32_bf16 v[36:39], v[126:129], v[102:105], v[36:39]
	s_waitcnt lgkmcnt(10)
	v_mfma_f32_16x16x32_bf16 v[32:35], v[130:133], v[102:105], v[32:35]
	v_mfma_f32_16x16x32_bf16 v[20:23], v[130:133], v[106:109], v[20:23]
	s_waitcnt lgkmcnt(8)
	v_mfma_f32_16x16x32_bf16 v[60:63], v[166:169], v[174:177], v[60:63]
	s_waitcnt lgkmcnt(7)
	v_mfma_f32_16x16x32_bf16 v[56:59], v[170:173], v[174:177], v[56:59]
	s_waitcnt lgkmcnt(6)
	v_mfma_f32_16x16x32_bf16 v[28:31], v[166:169], v[178:181], v[28:31]
	v_mfma_f32_16x16x32_bf16 v[24:27], v[170:173], v[178:181], v[24:27]
	s_waitcnt lgkmcnt(5)
	v_mfma_f32_16x16x32_bf16 v[16:19], v[182:185], v[178:181], v[16:19]
	v_mfma_f32_16x16x32_bf16 v[52:55], v[182:185], v[174:177], v[52:55]
	s_waitcnt lgkmcnt(4)
	v_mfma_f32_16x16x32_bf16 v[48:51], v[186:189], v[174:177], v[48:51]
	v_mfma_f32_16x16x32_bf16 v[12:15], v[186:189], v[178:181], v[12:15]
	s_waitcnt lgkmcnt(3)
	v_mfma_f32_16x16x32_bf16 v[8:11], v[190:193], v[178:181], v[8:11]
	v_mfma_f32_16x16x32_bf16 v[44:47], v[190:193], v[174:177], v[44:47]
	s_waitcnt lgkmcnt(2)
	v_mfma_f32_16x16x32_bf16 v[40:43], v[194:197], v[174:177], v[40:43]
	v_mfma_f32_16x16x32_bf16 v[4:7], v[194:197], v[178:181], v[4:7]
	s_waitcnt lgkmcnt(1)
	v_mfma_f32_16x16x32_bf16 v[0:3], v[198:201], v[178:181], v[0:3]
	v_mfma_f32_16x16x32_bf16 v[36:39], v[198:201], v[174:177], v[36:39]
	s_waitcnt lgkmcnt(0)
	v_mfma_f32_16x16x32_bf16 v[32:35], v[202:205], v[174:177], v[32:35]
	v_mfma_f32_16x16x32_bf16 v[20:23], v[202:205], v[178:181], v[20:23]
	s_cbranch_scc0 .LBB0_1006
	v_add_u32_e32 v138, s36, v80
	v_add_u32_e32 v126, v138, v81
	s_waitcnt vmcnt(0)
	s_barrier
	ds_read_b128 v[74:77], v126 offset:16384
	v_add3_u32 v102, s36, v81, v82
	ds_read_b128 v[94:97], v102
	ds_read_b128 v[98:101], v126 offset:18432
	ds_read_b128 v[102:105], v102 offset:2048
	ds_read_b128 v[106:109], v126 offset:20480
	ds_read_b128 v[110:113], v126 offset:22528
	ds_read_b128 v[114:117], v126 offset:24576
	ds_read_b128 v[118:121], v126 offset:26624
	v_add3_u32 v134, s36, v83, v82
	v_add_u32_e32 v142, v138, v83
	ds_read_b128 v[122:125], v126 offset:28672
	ds_read_b128 v[126:129], v126 offset:30720
	ds_read_b128 v[130:133], v134
	ds_read_b128 v[134:137], v134 offset:2048
	ds_read_b128 v[138:141], v142 offset:16384
	ds_read_b128 v[146:149], v142 offset:18432
	s_waitcnt lgkmcnt(11)
	v_mfma_f32_16x16x32_bf16 v[56:59], v[98:101], v[94:97], v[56:59]
	s_lshl_b32 s36, s34, 7
	s_lshl_b32 s26, s33, 7
	s_ashr_i32 s27, s26, 31
	v_mfma_f32_16x16x32_bf16 v[60:63], v[74:77], v[94:97], v[60:63]
	s_lshl_b64 s[26:27], s[26:27], 1
	s_add_i32 s31, s31, s28
	s_cmpk_gt_i32 s31, 0x107f
	s_waitcnt lgkmcnt(0)
	v_mfma_f32_16x16x32_bf16 v[56:59], v[146:149], v[130:133], v[56:59]
	v_mfma_f32_16x16x32_bf16 v[48:51], v[110:113], v[94:97], v[48:51]
	v_mfma_f32_16x16x32_bf16 v[52:55], v[106:109], v[94:97], v[52:55]
	s_nop 5
	v_max_f32_e32 v56, v56, v56
	v_max_f32_e32 v57, v57, v57
	v_max_f32_e32 v56, 0, v56
	v_mfma_f32_16x16x32_bf16 v[44:47], v[114:117], v[94:97], v[44:47]
	v_max_f32_e32 v57, 0, v57
	v_max_f32_e32 v59, v59, v59
	v_max_f32_e32 v59, 0, v59
	v_mfma_f32_16x16x32_bf16 v[40:43], v[118:121], v[94:97], v[40:43]
	v_mfma_f32_16x16x32_bf16 v[36:39], v[122:125], v[94:97], v[36:39]
	v_mfma_f32_16x16x32_bf16 v[32:35], v[126:129], v[94:97], v[32:35]
	ds_read_b128 v[94:97], v142 offset:20480
	ds_read_b128 v[150:153], v142 offset:22528
	ds_read_b128 v[154:157], v142 offset:24576
	ds_read_b128 v[158:161], v142 offset:26624
	v_mfma_f32_16x16x32_bf16 v[60:63], v[138:141], v[130:133], v[60:63]
	s_waitcnt lgkmcnt(2)
	v_mfma_f32_16x16x32_bf16 v[48:51], v[150:153], v[130:133], v[48:51]
	v_mfma_f32_16x16x32_bf16 v[16:19], v[106:109], v[102:105], v[16:19]
	v_mul_f32_e64 v106, v56, v56
	v_mul_f32_e64 v107, v57, v57
	v_max_f32_e32 v57, v58, v58
	s_nop 1
	v_max_f32_e32 v60, v60, v60
	v_mfma_f32_16x16x32_bf16 v[24:27], v[98:101], v[102:105], v[24:27]
	v_add_u32_e32 v100, s36, v79
	v_mov_b64_e32 v[98:99], s[0:1]
	v_max_f32_e32 v61, v61, v61
	v_max_f32_e32 v56, v62, v62
	v_max_f32_e32 v58, 0, v57
	v_max_f32_e32 v57, v63, v63
	v_mad_i64_i32 v[100:101], s[34:35], v100, s30, v[98:99]
	v_max_f32_e32 v60, 0, v60
	v_max_f32_e32 v61, 0, v61
	v_max_f32_e32 v56, 0, v56
	v_max_f32_e32 v57, 0, v57
	v_mfma_f32_16x16x32_bf16 v[52:55], v[94:97], v[130:133], v[52:55]
	v_lshl_add_u64 v[100:101], v[100:101], 0, s[26:27]
	v_pk_mul_f32 v[60:61], v[60:61], v[60:61]
	v_pk_mul_f32 v[62:63], v[56:57], v[56:57]
	v_mfma_f32_16x16x32_bf16 v[28:31], v[74:77], v[102:105], v[28:31]
	v_max_f32_e32 v48, v48, v48
	v_max_f32_e32 v49, v49, v49
	ds_read_b128 v[74:77], v142 offset:28672
	ds_read_b128 v[162:165], v142 offset:30720
	v_mfma_f32_16x16x32_bf16 v[12:15], v[110:113], v[102:105], v[12:15]
	v_lshl_add_u64 v[100:101], v[100:101], 0, v[64:65]
	v_cvt_pk_bf16_f32 v56, v60, v61
	v_cvt_pk_bf16_f32 v57, v62, v63
	v_mfma_f32_16x16x32_bf16 v[8:11], v[114:117], v[102:105], v[8:11]
	v_max_f32_e32 v48, 0, v48
	v_max_f32_e32 v49, 0, v49
	v_max_f32_e32 v52, v52, v52
	v_mfma_f32_16x16x32_bf16 v[4:7], v[118:121], v[102:105], v[4:7]
	v_max_f32_e32 v53, v53, v53
	v_max_f32_e32 v51, v51, v51
	v_max_f32_e32 v52, 0, v52
	v_mfma_f32_16x16x32_bf16 v[0:3], v[122:125], v[102:105], v[0:3]
	v_max_f32_e32 v53, 0, v53
	v_max_f32_e32 v51, 0, v51
	v_pk_mul_f32 v[52:53], v[52:53], v[52:53]
	v_mfma_f32_16x16x32_bf16 v[20:23], v[126:129], v[102:105], v[20:23]
	v_mul_f32_e64 v102, v58, v58
	v_mul_f32_e64 v103, v59, v59
	v_cvt_pk_bf16_f32 v58, v106, v107
	v_cvt_pk_bf16_f32 v59, v102, v103
	s_waitcnt lgkmcnt(2)
	v_mfma_f32_16x16x32_bf16 v[40:43], v[158:161], v[130:133], v[40:43]
	global_store_dwordx4 v[100:101], v[56:59], off
	s_nop 1
	v_pk_mul_f32 v[56:57], v[48:49], v[48:49]
	v_max_f32_e32 v49, v50, v50
	v_max_f32_e32 v48, v54, v54
	v_max_f32_e32 v50, 0, v49
	v_max_f32_e32 v49, v55, v55
	v_mfma_f32_16x16x32_bf16 v[44:47], v[154:157], v[130:133], v[44:47]
	v_max_f32_e32 v48, 0, v48
	v_max_f32_e32 v49, 0, v49
	v_pk_mul_f32 v[54:55], v[48:49], v[48:49]
	v_pk_mul_f32 v[58:59], v[50:51], v[50:51]
	v_max_f32_e32 v40, v40, v40
	v_max_f32_e32 v41, v41, v41
	s_waitcnt lgkmcnt(0)
	v_mfma_f32_16x16x32_bf16 v[32:35], v[162:165], v[130:133], v[32:35]
	v_cvt_pk_bf16_f32 v48, v52, v53
	v_cvt_pk_bf16_f32 v49, v54, v55
	v_cvt_pk_bf16_f32 v50, v56, v57
	v_cvt_pk_bf16_f32 v51, v58, v59
	v_max_f32_e32 v40, 0, v40
	v_max_f32_e32 v41, 0, v41
	global_store_dwordx4 v[100:101], v[48:51], off offset:64
	v_max_f32_e32 v44, v44, v44
	v_max_f32_e32 v45, v45, v45
	v_pk_mul_f32 v[48:49], v[40:41], v[40:41]
	v_max_f32_e32 v41, v42, v42
	v_max_f32_e32 v40, v46, v46
	v_max_f32_e32 v42, 0, v41
	v_max_f32_e32 v41, v47, v47
	v_max_f32_e32 v43, v43, v43
	v_mfma_f32_16x16x32_bf16 v[36:39], v[74:77], v[130:133], v[36:39]
	v_max_f32_e32 v44, 0, v44
	v_max_f32_e32 v45, 0, v45
	v_max_f32_e32 v40, 0, v40
	v_max_f32_e32 v41, 0, v41
	v_max_f32_e32 v43, 0, v43
	v_pk_mul_f32 v[44:45], v[44:45], v[44:45]
	v_pk_mul_f32 v[46:47], v[40:41], v[40:41]
	v_pk_mul_f32 v[50:51], v[42:43], v[42:43]
	v_max_f32_e32 v32, v32, v32
	v_max_f32_e32 v33, v33, v33
	v_mfma_f32_16x16x32_bf16 v[24:27], v[146:149], v[134:137], v[24:27]
	v_cvt_pk_bf16_f32 v40, v44, v45
	v_cvt_pk_bf16_f32 v41, v46, v47
	v_cvt_pk_bf16_f32 v42, v48, v49
	v_cvt_pk_bf16_f32 v43, v50, v51
	v_max_f32_e32 v32, 0, v32
	v_max_f32_e32 v33, 0, v33
	global_store_dwordx4 v[100:101], v[40:43], off offset:128
	v_max_f32_e32 v36, v36, v36
	v_max_f32_e32 v37, v37, v37
	v_pk_mul_f32 v[40:41], v[32:33], v[32:33]
	v_max_f32_e32 v33, v34, v34
	v_max_f32_e32 v32, v38, v38
	v_max_f32_e32 v34, 0, v33
	v_max_f32_e32 v33, v39, v39
	v_max_f32_e32 v35, v35, v35
	v_mfma_f32_16x16x32_bf16 v[28:31], v[138:141], v[134:137], v[28:31]
	v_max_f32_e32 v36, 0, v36
	v_max_f32_e32 v37, 0, v37
	v_max_f32_e32 v32, 0, v32
	v_max_f32_e32 v33, 0, v33
	v_max_f32_e32 v35, 0, v35
	v_pk_mul_f32 v[36:37], v[36:37], v[36:37]
	v_pk_mul_f32 v[38:39], v[32:33], v[32:33]
	v_pk_mul_f32 v[42:43], v[34:35], v[34:35]
	v_max_f32_e32 v24, v24, v24
	v_max_f32_e32 v25, v25, v25
	v_mfma_f32_16x16x32_bf16 v[12:15], v[150:153], v[134:137], v[12:15]
	v_cvt_pk_bf16_f32 v32, v36, v37
	v_cvt_pk_bf16_f32 v33, v38, v39
	v_cvt_pk_bf16_f32 v34, v40, v41
	v_cvt_pk_bf16_f32 v35, v42, v43
	v_max_f32_e32 v24, 0, v24
	v_max_f32_e32 v25, 0, v25
	global_store_dwordx4 v[100:101], v[32:35], off offset:192
	v_max_f32_e32 v28, v28, v28
	v_max_f32_e32 v29, v29, v29
	v_pk_mul_f32 v[34:35], v[24:25], v[24:25]
	v_max_f32_e32 v25, v26, v26
	v_add_u32_e32 v32, s36, v84
	v_max_f32_e32 v24, v30, v30
	v_max_f32_e32 v26, 0, v25
	v_max_f32_e32 v25, v31, v31
	v_max_f32_e32 v27, v27, v27
	v_mfma_f32_16x16x32_bf16 v[16:19], v[94:97], v[134:137], v[16:19]
	v_mad_i64_i32 v[32:33], s[34:35], v32, s30, v[98:99]
	v_max_f32_e32 v28, 0, v28
	v_max_f32_e32 v29, 0, v29
	v_max_f32_e32 v24, 0, v24
	v_max_f32_e32 v25, 0, v25
	v_max_f32_e32 v27, 0, v27
	v_lshl_add_u64 v[32:33], v[32:33], 0, s[26:27]
	v_pk_mul_f32 v[28:29], v[28:29], v[28:29]
	v_pk_mul_f32 v[30:31], v[24:25], v[24:25]
	v_pk_mul_f32 v[36:37], v[26:27], v[26:27]
	v_max_f32_e32 v12, v12, v12
	v_max_f32_e32 v13, v13, v13
	v_mfma_f32_16x16x32_bf16 v[4:7], v[158:161], v[134:137], v[4:7]
	v_lshl_add_u64 v[32:33], v[32:33], 0, v[64:65]
	v_cvt_pk_bf16_f32 v24, v28, v29
	v_cvt_pk_bf16_f32 v25, v30, v31
	v_cvt_pk_bf16_f32 v26, v34, v35
	v_cvt_pk_bf16_f32 v27, v36, v37
	v_max_f32_e32 v12, 0, v12
	v_max_f32_e32 v13, 0, v13
	global_store_dwordx4 v[32:33], v[24:27], off
	v_max_f32_e32 v16, v16, v16
	v_max_f32_e32 v17, v17, v17
	v_pk_mul_f32 v[24:25], v[12:13], v[12:13]
	v_max_f32_e32 v13, v14, v14
	v_max_f32_e32 v12, v18, v18
	v_max_f32_e32 v14, 0, v13
	v_max_f32_e32 v13, v19, v19
	v_max_f32_e32 v15, v15, v15
	v_mfma_f32_16x16x32_bf16 v[8:11], v[154:157], v[134:137], v[8:11]
	v_max_f32_e32 v16, 0, v16
	v_max_f32_e32 v17, 0, v17
	v_max_f32_e32 v12, 0, v12
	v_max_f32_e32 v13, 0, v13
	v_max_f32_e32 v15, 0, v15
	v_pk_mul_f32 v[16:17], v[16:17], v[16:17]
	v_pk_mul_f32 v[18:19], v[12:13], v[12:13]
	v_pk_mul_f32 v[26:27], v[14:15], v[14:15]
	v_max_f32_e32 v4, v4, v4
	v_max_f32_e32 v5, v5, v5
	v_cvt_pk_bf16_f32 v12, v16, v17
	v_cvt_pk_bf16_f32 v13, v18, v19
	v_cvt_pk_bf16_f32 v14, v24, v25
	v_cvt_pk_bf16_f32 v15, v26, v27
	v_max_f32_e32 v4, 0, v4
	v_max_f32_e32 v5, 0, v5
	global_store_dwordx4 v[32:33], v[12:15], off offset:64
	v_mfma_f32_16x16x32_bf16 v[0:3], v[74:77], v[134:137], v[0:3]
	v_max_f32_e32 v8, v8, v8
	v_pk_mul_f32 v[12:13], v[4:5], v[4:5]
	v_max_f32_e32 v5, v6, v6
	v_mfma_f32_16x16x32_bf16 v[20:23], v[162:165], v[134:137], v[20:23]
	v_max_f32_e32 v9, v9, v9
	v_max_f32_e32 v4, v10, v10
	v_max_f32_e32 v6, 0, v5
	v_max_f32_e32 v5, v11, v11
	v_max_f32_e32 v7, v7, v7
	v_max_f32_e32 v8, 0, v8
	v_max_f32_e32 v9, 0, v9
	v_max_f32_e32 v4, 0, v4
	v_max_f32_e32 v5, 0, v5
	v_max_f32_e32 v7, 0, v7
	v_pk_mul_f32 v[8:9], v[8:9], v[8:9]
	v_pk_mul_f32 v[10:11], v[4:5], v[4:5]
	v_pk_mul_f32 v[14:15], v[6:7], v[6:7]
	v_cvt_pk_bf16_f32 v4, v8, v9
	v_cvt_pk_bf16_f32 v5, v10, v11
	v_cvt_pk_bf16_f32 v6, v12, v13
	v_cvt_pk_bf16_f32 v7, v14, v15
	global_store_dwordx4 v[32:33], v[4:7], off offset:128
	v_max_f32_e32 v0, v0, v0
	v_max_f32_e32 v1, v1, v1
	v_max_f32_e32 v4, v20, v20
	v_max_f32_e32 v5, v21, v21
	v_max_f32_e32 v2, v2, v2
	v_max_f32_e32 v6, v22, v22
	v_max_f32_e32 v3, v3, v3
	v_max_f32_e32 v7, v23, v23
	v_max_f32_e32 v0, 0, v0
	v_max_f32_e32 v4, 0, v4
	v_max_f32_e32 v1, 0, v1
	v_max_f32_e32 v5, 0, v5
	v_max_f32_e32 v2, 0, v2
	v_max_f32_e32 v6, 0, v6
	v_max_f32_e32 v3, 0, v3
	v_max_f32_e32 v7, 0, v7
	v_pk_mul_f32 v[0:1], v[0:1], v[0:1]
	v_pk_mul_f32 v[4:5], v[4:5], v[4:5]
	v_pk_mul_f32 v[2:3], v[2:3], v[2:3]
	v_pk_mul_f32 v[6:7], v[6:7], v[6:7]
	v_cvt_pk_bf16_f32 v0, v0, v1
	v_cvt_pk_bf16_f32 v1, v2, v3
	v_cvt_pk_bf16_f32 v2, v4, v5
	v_cvt_pk_bf16_f32 v3, v6, v7
	global_store_dwordx4 v[32:33], v[0:3], off offset:192
	s_cbranch_scc0 .LBB0_1005

.LBB0_1071:
	s_add_i32 s45, s43, 0x8000
	s_and_b32 s44, s45, 0x8000
	s_add_i32 s44, s44, 0
	s_add_u32 s86, s44, s87
	s_mov_b32 m0, s86
	s_waitcnt vmcnt(0) lgkmcnt(0)
	s_barrier
	global_load_lds_dwordx4 v244, s[96:97]
	s_add_u32 m0, s86, 0x4000
	s_nop 0
	global_load_lds_dwordx4 v245, s[88:89]
	s_add_u32 m0, s86, 0x1000
	s_nop 0
	global_load_lds_dwordx4 v246, s[96:97]
	s_add_u32 m0, s86, 0x5000
	s_nop 0
	global_load_lds_dwordx4 v247, s[88:89]
	s_add_u32 m0, s86, 0x2000
	s_nop 0
	global_load_lds_dwordx4 v248, s[96:97]
	s_add_u32 m0, s86, 0x6000
	s_nop 0
	global_load_lds_dwordx4 v249, s[88:89]
	s_add_u32 m0, s86, 0x3000
	s_nop 0
	global_load_lds_dwordx4 v250, s[96:97]
	s_add_u32 m0, s86, 0x7000
	s_nop 0
	global_load_lds_dwordx4 v251, s[88:89]
	s_add_u32 s96, s96, 0x80
	s_addc_u32 s97, s97, 0
	s_add_u32 s88, s88, 0x80
	s_addc_u32 s89, s89, 0
	s_and_b32 s43, s43, 0x8000
	s_add_i32 s43, s43, 0
	v_add3_u32 v169, s43, v84, v89
	v_add3_u32 v210, s43, v89, v90
	v_add3_u32 v211, s43, v84, v91
	v_add3_u32 v212, s43, v90, v91
	ds_read_b128 v[106:109], v210
	ds_read_b128 v[76:79], v169 offset:16384
	ds_read_b128 v[102:105], v169 offset:18432
	ds_read_b128 v[110:113], v210 offset:2048
	ds_read_b128 v[114:117], v169 offset:20480
	ds_read_b128 v[118:121], v169 offset:22528
	ds_read_b128 v[122:125], v169 offset:24576
	ds_read_b128 v[126:129], v169 offset:26624
	ds_read_b128 v[130:133], v169 offset:28672
	ds_read_b128 v[134:137], v169 offset:30720
	ds_read_b128 v[178:181], v212
	ds_read_b128 v[170:173], v211 offset:16384
	ds_read_b128 v[174:177], v211 offset:18432
	ds_read_b128 v[182:185], v212 offset:2048
	ds_read_b128 v[186:189], v211 offset:20480
	ds_read_b128 v[190:193], v211 offset:22528
	ds_read_b128 v[194:197], v211 offset:24576
	ds_read_b128 v[198:201], v211 offset:26624
	ds_read_b128 v[202:205], v211 offset:28672
	ds_read_b128 v[206:209], v211 offset:30720
	s_add_u32 s34, s34, 0x80
	s_addc_u32 s35, s35, 0
	s_cmpk_eq_i32 s34, 0x1f80
	s_mov_b32 s43, s45
	s_waitcnt lgkmcnt(15)
	v_mfma_f32_16x16x32_bf16 v[60:63], v[76:79], v[106:109], v[60:63]
	v_mfma_f32_16x16x32_bf16 v[56:59], v[102:105], v[106:109], v[56:59]
	v_mfma_f32_16x16x32_bf16 v[24:27], v[76:79], v[110:113], v[24:27]
	v_mfma_f32_16x16x32_bf16 v[20:23], v[102:105], v[110:113], v[20:23]
	v_mfma_f32_16x16x32_bf16 v[16:19], v[114:117], v[110:113], v[16:19]
	v_mfma_f32_16x16x32_bf16 v[52:55], v[114:117], v[106:109], v[52:55]
	s_waitcnt lgkmcnt(14)
	v_mfma_f32_16x16x32_bf16 v[48:51], v[118:121], v[106:109], v[48:51]
	v_mfma_f32_16x16x32_bf16 v[12:15], v[118:121], v[110:113], v[12:15]
	s_waitcnt lgkmcnt(13)
	v_mfma_f32_16x16x32_bf16 v[8:11], v[122:125], v[110:113], v[8:11]
	v_mfma_f32_16x16x32_bf16 v[44:47], v[122:125], v[106:109], v[44:47]
	s_waitcnt lgkmcnt(12)
	v_mfma_f32_16x16x32_bf16 v[40:43], v[126:129], v[106:109], v[40:43]
	v_mfma_f32_16x16x32_bf16 v[4:7], v[126:129], v[110:113], v[4:7]
	s_waitcnt lgkmcnt(11)
	v_mfma_f32_16x16x32_bf16 v[0:3], v[130:133], v[110:113], v[0:3]
	v_mfma_f32_16x16x32_bf16 v[32:35], v[130:133], v[106:109], v[32:35]
	s_waitcnt lgkmcnt(10)
	v_mfma_f32_16x16x32_bf16 v[28:31], v[134:137], v[106:109], v[28:31]
	v_mfma_f32_16x16x32_bf16 v[36:39], v[134:137], v[110:113], v[36:39]
	s_waitcnt lgkmcnt(8)
	v_mfma_f32_16x16x32_bf16 v[60:63], v[170:173], v[178:181], v[60:63]
	s_waitcnt lgkmcnt(7)
	v_mfma_f32_16x16x32_bf16 v[56:59], v[174:177], v[178:181], v[56:59]
	s_waitcnt lgkmcnt(6)
	v_mfma_f32_16x16x32_bf16 v[24:27], v[170:173], v[182:185], v[24:27]
	v_mfma_f32_16x16x32_bf16 v[20:23], v[174:177], v[182:185], v[20:23]
	s_waitcnt lgkmcnt(5)
	v_mfma_f32_16x16x32_bf16 v[16:19], v[186:189], v[182:185], v[16:19]
	v_mfma_f32_16x16x32_bf16 v[52:55], v[186:189], v[178:181], v[52:55]
	s_waitcnt lgkmcnt(4)
	v_mfma_f32_16x16x32_bf16 v[48:51], v[190:193], v[178:181], v[48:51]
	v_mfma_f32_16x16x32_bf16 v[12:15], v[190:193], v[182:185], v[12:15]
	s_waitcnt lgkmcnt(3)
	v_mfma_f32_16x16x32_bf16 v[8:11], v[194:197], v[182:185], v[8:11]
	v_mfma_f32_16x16x32_bf16 v[44:47], v[194:197], v[178:181], v[44:47]
	s_waitcnt lgkmcnt(2)
	v_mfma_f32_16x16x32_bf16 v[40:43], v[198:201], v[178:181], v[40:43]
	v_mfma_f32_16x16x32_bf16 v[4:7], v[198:201], v[182:185], v[4:7]
	s_waitcnt lgkmcnt(1)
	v_mfma_f32_16x16x32_bf16 v[0:3], v[202:205], v[182:185], v[0:3]
	v_mfma_f32_16x16x32_bf16 v[32:35], v[202:205], v[178:181], v[32:35]
	s_waitcnt lgkmcnt(0)
	v_mfma_f32_16x16x32_bf16 v[28:31], v[206:209], v[178:181], v[28:31]
	v_mfma_f32_16x16x32_bf16 v[36:39], v[206:209], v[182:185], v[36:39]
	s_cbranch_scc0 .LBB0_1071
	v_add_u32_e32 v80, s44, v84
	v_add_u32_e32 v81, v80, v89
	v_add3_u32 v106, s44, v89, v90
	s_waitcnt vmcnt(0)
	s_barrier
	ds_read_b128 v[72:75], v81 offset:16384
	ds_read_b128 v[76:79], v81 offset:18432
	ds_read_b128 v[102:105], v106
	ds_read_b128 v[106:109], v106 offset:2048
	ds_read_b128 v[110:113], v81 offset:20480
	ds_read_b128 v[114:117], v81 offset:22528
	ds_read_b128 v[118:121], v81 offset:24576
	ds_read_b128 v[122:125], v81 offset:26624
	ds_read_b128 v[126:129], v81 offset:28672
	ds_read_b128 v[130:133], v81 offset:30720
	v_add_u32_e32 v80, v80, v91
	s_waitcnt lgkmcnt(7)
	v_mfma_f32_16x16x32_bf16 v[60:63], v[72:75], v[102:105], v[60:63]
	s_lshl_b32 s42, s42, 7
	v_mfma_f32_16x16x32_bf16 v[56:59], v[76:79], v[102:105], v[56:59]
	s_waitcnt lgkmcnt(4)
	v_mfma_f32_16x16x32_bf16 v[48:51], v[114:117], v[102:105], v[48:51]
	s_waitcnt lgkmcnt(3)
	v_mfma_f32_16x16x32_bf16 v[44:47], v[118:121], v[102:105], v[44:47]
	s_waitcnt lgkmcnt(2)
	v_mfma_f32_16x16x32_bf16 v[40:43], v[122:125], v[102:105], v[40:43]
	s_waitcnt lgkmcnt(1)
	v_mfma_f32_16x16x32_bf16 v[32:35], v[126:129], v[102:105], v[32:35]
	s_waitcnt lgkmcnt(0)
	v_mfma_f32_16x16x32_bf16 v[28:31], v[130:133], v[102:105], v[28:31]
	v_mfma_f32_16x16x32_bf16 v[24:27], v[72:75], v[106:109], v[24:27]
	ds_read_b128 v[72:75], v80 offset:16384
	v_mfma_f32_16x16x32_bf16 v[52:55], v[110:113], v[102:105], v[52:55]
	v_mfma_f32_16x16x32_bf16 v[20:23], v[76:79], v[106:109], v[20:23]
	v_mfma_f32_16x16x32_bf16 v[16:19], v[110:113], v[106:109], v[16:19]
	v_mfma_f32_16x16x32_bf16 v[12:15], v[114:117], v[106:109], v[12:15]
	v_mfma_f32_16x16x32_bf16 v[8:11], v[118:121], v[106:109], v[8:11]
	v_mfma_f32_16x16x32_bf16 v[4:7], v[122:125], v[106:109], v[4:7]
	v_mfma_f32_16x16x32_bf16 v[0:3], v[126:129], v[106:109], v[0:3]
	v_mfma_f32_16x16x32_bf16 v[102:105], v[130:133], v[106:109], v[36:39]
	s_nop 2
	v_add3_u32 v36, s44, v91, v90
	ds_read_b128 v[76:79], v80 offset:18432
	ds_read_b128 v[106:109], v36
	ds_read_b128 v[110:113], v36 offset:2048
	ds_read_b128 v[130:133], v80 offset:28672
	ds_read_b128 v[134:137], v80 offset:30720
	ds_read_b128 v[114:117], v80 offset:20480
	ds_read_b128 v[118:121], v80 offset:22528
	ds_read_b128 v[122:125], v80 offset:24576
	ds_read_b128 v[126:129], v80 offset:26624
	s_waitcnt lgkmcnt(7)
	v_mfma_f32_16x16x32_bf16 v[60:63], v[72:75], v[106:109], v[60:63]
	s_waitcnt lgkmcnt(5)
	v_mfma_f32_16x16x32_bf16 v[36:39], v[130:133], v[106:109], v[32:35]
	s_waitcnt lgkmcnt(4)
	v_mfma_f32_16x16x32_bf16 v[32:35], v[134:137], v[106:109], v[28:31]
	v_mfma_f32_16x16x32_bf16 v[28:31], v[72:75], v[110:113], v[24:27]
	v_add_u32_e32 v72, s42, v85
	v_mul_hi_i32 v73, v72, s36
	v_mfma_f32_16x16x32_bf16 v[24:27], v[76:79], v[110:113], v[20:23]
	s_waitcnt lgkmcnt(3)
	v_mfma_f32_16x16x32_bf16 v[20:23], v[114:117], v[110:113], v[16:19]
	s_waitcnt lgkmcnt(2)
	v_mfma_f32_16x16x32_bf16 v[16:19], v[118:121], v[110:113], v[12:15]
	s_waitcnt lgkmcnt(1)
	v_mfma_f32_16x16x32_bf16 v[12:15], v[122:125], v[110:113], v[8:11]
	s_waitcnt lgkmcnt(0)
	v_mfma_f32_16x16x32_bf16 v[8:11], v[126:129], v[110:113], v[4:7]
	s_nop 2
	v_lshrrev_b32_e32 v4, 31, v73
	v_ashrrev_i32_e32 v5, 11, v73
	v_mfma_f32_16x16x32_bf16 v[56:59], v[76:79], v[106:109], v[56:59]
	v_add_u32_e32 v73, v5, v4
	v_mad_i32_i24 v78, v73, s37, v72
	v_lshlrev_b32_e32 v75, 13, v73
	v_mfma_f32_16x16x32_bf16 v[52:55], v[114:117], v[106:109], v[52:55]
	v_cmp_lt_i32_e32 vcc, s38, v78
	v_add3_u32 v74, v75, v78, s39
	v_mfma_f32_16x16x32_bf16 v[48:51], v[118:121], v[106:109], v[48:51]
	v_mfma_f32_16x16x32_bf16 v[44:47], v[122:125], v[106:109], v[44:47]
	v_mfma_f32_16x16x32_bf16 v[40:43], v[126:129], v[106:109], v[40:43]
	v_mfma_f32_16x16x32_bf16 v[4:7], v[130:133], v[110:113], v[0:3]
	v_mfma_f32_16x16x32_bf16 v[0:3], v[134:137], v[110:113], v[102:105]
	s_and_saveexec_b64 s[34:35], vcc
	s_xor_b64 s[34:35], exec, s[34:35]
	v_add3_u32 v72, v75, v78, s39
	s_or_saveexec_b64 s[34:35], s[34:35]
	v_mov_b64_e32 v[76:77], s[92:93]
	v_lshl_add_u32 v75, v73, 8, v78
	s_xor_b64 exec, exec, s[34:35]
	v_lshl_add_u32 v72, v73, 8, v78
	v_mov_b64_e32 v[76:77], s[6:7]
	s_or_b64 exec, exec, s[34:35]
	s_and_saveexec_b64 s[34:35], vcc
	s_xor_b64 s[34:35], exec, s[34:35]
	s_cbranch_execz .LBB0_1078
	v_mul_hi_i32_i24_e32 v79, 0x6000, v73
	v_mul_i32_i24_e32 v78, 0x6000, v73
	s_or_saveexec_b64 s[34:35], s[34:35]
	v_mov_b64_e32 v[80:81], s[92:93]
	s_xor_b64 exec, exec, s[34:35]
	s_cbranch_execnz .LBB0_1079
	s_branch .LBB0_1080

.LBB0_1091:
	s_add_i32 s48, s47, 0x8000
	s_and_b32 s8, s47, 0x8000
	s_and_b32 s47, s48, 0x8000
	s_add_i32 s49, s8, 0
	s_add_i32 s8, s47, 0
	s_add_u32 s71, s8, s75
	s_mov_b32 m0, s71
	s_waitcnt vmcnt(0) lgkmcnt(0)
	s_barrier
	global_load_lds_dwordx4 v236, s[84:85]
	s_add_u32 m0, s71, 0x4000
	s_nop 0
	global_load_lds_dwordx4 v237, s[72:73]
	s_add_u32 m0, s71, 0x1000
	s_nop 0
	global_load_lds_dwordx4 v238, s[84:85]
	s_add_u32 m0, s71, 0x5000
	s_nop 0
	global_load_lds_dwordx4 v239, s[72:73]
	s_add_u32 m0, s71, 0x2000
	s_nop 0
	global_load_lds_dwordx4 v240, s[84:85]
	s_add_u32 m0, s71, 0x6000
	s_nop 0
	global_load_lds_dwordx4 v241, s[72:73]
	s_add_u32 m0, s71, 0x3000
	s_nop 0
	global_load_lds_dwordx4 v242, s[84:85]
	s_add_u32 m0, s71, 0x7000
	s_nop 0
	global_load_lds_dwordx4 v243, s[72:73]
	s_add_u32 s84, s84, 0x80
	s_addc_u32 s85, s85, 0
	s_add_u32 s72, s72, 0x80
	s_addc_u32 s73, s73, 0
	v_add3_u32 v169, s49, v84, v87
	v_add3_u32 v210, s49, v87, v89
	v_add3_u32 v211, s49, v84, v90
	v_add3_u32 v212, s49, v89, v90
	ds_read_b128 v[104:107], v210
	ds_read_b128 v[68:71], v169 offset:16384
	ds_read_b128 v[100:103], v169 offset:18432
	ds_read_b128 v[108:111], v210 offset:2048
	ds_read_b128 v[112:115], v169 offset:20480
	ds_read_b128 v[116:119], v169 offset:22528
	ds_read_b128 v[120:123], v169 offset:24576
	ds_read_b128 v[124:127], v169 offset:26624
	ds_read_b128 v[128:131], v169 offset:28672
	ds_read_b128 v[132:135], v169 offset:30720
	ds_read_b128 v[178:181], v212
	ds_read_b128 v[170:173], v211 offset:16384
	ds_read_b128 v[174:177], v211 offset:18432
	ds_read_b128 v[182:185], v212 offset:2048
	ds_read_b128 v[186:189], v211 offset:20480
	ds_read_b128 v[190:193], v211 offset:22528
	ds_read_b128 v[194:197], v211 offset:24576
	ds_read_b128 v[198:201], v211 offset:26624
	ds_read_b128 v[202:205], v211 offset:28672
	ds_read_b128 v[206:209], v211 offset:30720
	s_add_u32 s36, s36, 0x80
	s_addc_u32 s37, s37, 0
	s_cmpk_eq_i32 s36, 0x780
	s_mov_b32 s47, s48
	s_waitcnt lgkmcnt(15)
	v_mfma_f32_16x16x32_bf16 v[60:63], v[68:71], v[104:107], v[60:63]
	v_mfma_f32_16x16x32_bf16 v[56:59], v[100:103], v[104:107], v[56:59]
	v_mfma_f32_16x16x32_bf16 v[28:31], v[68:71], v[108:111], v[28:31]
	v_mfma_f32_16x16x32_bf16 v[24:27], v[100:103], v[108:111], v[24:27]
	v_mfma_f32_16x16x32_bf16 v[16:19], v[112:115], v[108:111], v[16:19]
	v_mfma_f32_16x16x32_bf16 v[52:55], v[112:115], v[104:107], v[52:55]
	s_waitcnt lgkmcnt(14)
	v_mfma_f32_16x16x32_bf16 v[48:51], v[116:119], v[104:107], v[48:51]
	v_mfma_f32_16x16x32_bf16 v[12:15], v[116:119], v[108:111], v[12:15]
	s_waitcnt lgkmcnt(13)
	v_mfma_f32_16x16x32_bf16 v[8:11], v[120:123], v[108:111], v[8:11]
	v_mfma_f32_16x16x32_bf16 v[44:47], v[120:123], v[104:107], v[44:47]
	s_waitcnt lgkmcnt(12)
	v_mfma_f32_16x16x32_bf16 v[40:43], v[124:127], v[104:107], v[40:43]
	v_mfma_f32_16x16x32_bf16 v[4:7], v[124:127], v[108:111], v[4:7]
	s_waitcnt lgkmcnt(11)
	v_mfma_f32_16x16x32_bf16 v[0:3], v[128:131], v[108:111], v[0:3]
	v_mfma_f32_16x16x32_bf16 v[36:39], v[128:131], v[104:107], v[36:39]
	s_waitcnt lgkmcnt(10)
	v_mfma_f32_16x16x32_bf16 v[32:35], v[132:135], v[104:107], v[32:35]
	v_mfma_f32_16x16x32_bf16 v[20:23], v[132:135], v[108:111], v[20:23]
	s_waitcnt lgkmcnt(8)
	v_mfma_f32_16x16x32_bf16 v[60:63], v[170:173], v[178:181], v[60:63]
	s_waitcnt lgkmcnt(7)
	v_mfma_f32_16x16x32_bf16 v[56:59], v[174:177], v[178:181], v[56:59]
	s_waitcnt lgkmcnt(6)
	v_mfma_f32_16x16x32_bf16 v[28:31], v[170:173], v[182:185], v[28:31]
	v_mfma_f32_16x16x32_bf16 v[24:27], v[174:177], v[182:185], v[24:27]
	s_waitcnt lgkmcnt(5)
	v_mfma_f32_16x16x32_bf16 v[16:19], v[186:189], v[182:185], v[16:19]
	v_mfma_f32_16x16x32_bf16 v[52:55], v[186:189], v[178:181], v[52:55]
	s_waitcnt lgkmcnt(4)
	v_mfma_f32_16x16x32_bf16 v[48:51], v[190:193], v[178:181], v[48:51]
	v_mfma_f32_16x16x32_bf16 v[12:15], v[190:193], v[182:185], v[12:15]
	s_waitcnt lgkmcnt(3)
	v_mfma_f32_16x16x32_bf16 v[8:11], v[194:197], v[182:185], v[8:11]
	v_mfma_f32_16x16x32_bf16 v[44:47], v[194:197], v[178:181], v[44:47]
	s_waitcnt lgkmcnt(2)
	v_mfma_f32_16x16x32_bf16 v[40:43], v[198:201], v[178:181], v[40:43]
	v_mfma_f32_16x16x32_bf16 v[4:7], v[198:201], v[182:185], v[4:7]
	s_waitcnt lgkmcnt(1)
	v_mfma_f32_16x16x32_bf16 v[0:3], v[202:205], v[182:185], v[0:3]
	v_mfma_f32_16x16x32_bf16 v[36:39], v[202:205], v[178:181], v[36:39]
	s_waitcnt lgkmcnt(0)
	v_mfma_f32_16x16x32_bf16 v[32:35], v[206:209], v[178:181], v[32:35]
	v_mfma_f32_16x16x32_bf16 v[20:23], v[206:209], v[182:185], v[20:23]
	s_cbranch_scc0 .LBB0_1091
	v_lshl_add_u32 v99, s46, 7, v85
	v_mul_hi_i32 v64, v99, s39
	v_lshrrev_b32_e32 v65, 31, v64
	v_ashrrev_i32_e32 v64, 11, v64
	v_add_u32_e32 v64, v64, v65
	v_mad_i32_i24 v65, v64, s40, v99
	v_cmp_lt_i32_e32 vcc, s41, v65
	v_lshl_or_b32 v72, s45, 9, v86
	s_waitcnt vmcnt(0)
	v_cndmask_b32_e32 v64, 2, v64, vcc
	v_mul_hi_i32_i24_e32 v65, 0x6000, v64
	v_mul_i32_i24_e32 v64, 0x6000, v64
	v_lshl_add_u64 v[64:65], s[94:95], 0, v[64:65]
	v_lshl_add_u64 v[150:151], v[64:65], 0, s[34:35]
	v_lshl_add_u64 v[64:65], v[150:151], 0, v[72:73]
	s_barrier
	global_load_dwordx4 v[172:175], v[64:65], off
	global_load_dwordx4 v[176:179], v[64:65], off offset:16
	global_load_dwordx4 v[180:183], v[64:65], off offset:128
	global_load_dwordx4 v[184:187], v[64:65], off offset:144
	global_load_dwordx4 v[188:191], v[64:65], off offset:256
	global_load_dwordx4 v[192:195], v[64:65], off offset:272
	global_load_dwordx4 v[196:199], v[64:65], off offset:384
	global_load_dwordx4 v[200:203], v[64:65], off offset:400
	v_or_b32_e32 v238, 16, v99
	v_mul_hi_i32 v236, v238, s39
	v_lshrrev_b32_e32 v237, 31, v236
	v_ashrrev_i32_e32 v236, 11, v236
	v_add_u32_e32 v236, v236, v237
	v_mad_i32_i24 v237, v236, s40, v238
	v_cmp_lt_i32_e64 s[52:53], s41, v237
	v_cndmask_b32_e64 v236, 2, v236, s[52:53]
	v_mul_hi_i32_i24_e32 v237, 0x6000, v236
	v_mul_i32_i24_e32 v236, 0x6000, v236
	v_lshl_add_u64 v[238:239], s[94:95], 0, v[236:237]
	v_lshl_add_u64 v[238:239], v[238:239], 0, s[34:35]
	v_lshl_add_u64 v[238:239], v[238:239], 0, v[72:73]
	global_load_dwordx4 v[204:207], v[238:239], off
	global_load_dwordx4 v[208:211], v[238:239], off offset:16
	global_load_dwordx4 v[212:215], v[238:239], off offset:128
	global_load_dwordx4 v[216:219], v[238:239], off offset:144
	global_load_dwordx4 v[220:223], v[238:239], off offset:256
	global_load_dwordx4 v[224:227], v[238:239], off offset:272
	global_load_dwordx4 v[228:231], v[238:239], off offset:384
	global_load_dwordx4 v[232:235], v[238:239], off offset:400
	v_add3_u32 v64, s8, v87, v89
	v_add_u32_e32 v68, s8, v84
	ds_read_b128 v[104:107], v64
	ds_read_b128 v[108:111], v64 offset:2048
	v_add3_u32 v65, s8, v90, v89
	v_add_u32_e32 v145, v68, v87
	ds_read_b128 v[112:115], v65
	ds_read_b128 v[64:67], v65 offset:2048
	v_add_u32_e32 v168, v68, v90
	ds_read_b128 v[116:119], v145 offset:16384
	ds_read_b128 v[120:123], v145 offset:18432
	ds_read_b128 v[124:127], v168 offset:16384
	ds_read_b128 v[68:71], v168 offset:18432
	v_mul_hi_i32 v128, v99, s38
	s_waitcnt lgkmcnt(3)
	v_mfma_f32_16x16x32_bf16 v[60:63], v[116:119], v[104:107], v[60:63]
	v_lshrrev_b32_e32 v129, 31, v128
	v_lshrrev_b32_e32 v128, 11, v128
	v_add_u32_e32 v128, v128, v129
	v_lshl_add_u32 v128, v128, 13, v99
	s_lshl_b32 s8, s44, 9
	v_ashrrev_i32_e32 v129, 31, v128
	s_waitcnt lgkmcnt(1)
	v_mfma_f32_16x16x32_bf16 v[60:63], v[124:127], v[112:115], v[60:63]
	v_lshl_add_u64 v[128:129], v[128:129], 0, s[8:9]
	v_lshlrev_b64 v[128:129], 12, v[128:129]
	v_lshl_add_u64 v[128:129], s[6:7], 0, v[128:129]
	v_mov_b32_e32 v153, v73
	v_or_b32_e32 v152, 16, v72
	v_lshl_add_u64 v[154:155], v[128:129], 0, v[72:73]
	v_lshl_add_u64 v[128:129], v[150:151], 0, v[152:153]
	v_mfma_f32_16x16x32_bf16 v[56:59], v[120:123], v[104:107], v[56:59]
	v_mov_b32_e32 v157, v73
	v_or_b32_e32 v156, 0x80, v72
	v_mov_b32_e32 v159, v73
	s_waitcnt lgkmcnt(0)
	v_mfma_f32_16x16x32_bf16 v[56:59], v[68:71], v[112:115], v[56:59]
	v_or_b32_e32 v158, 0x90, v72
	v_lshl_add_u64 v[136:137], v[150:151], 0, v[158:159]
	v_mov_b32_e32 v161, v73
	v_or_b32_e32 v160, 0x100, v72
	v_mov_b32_e32 v163, v73
	v_or_b32_e32 v162, 0x110, v72
	v_lshl_add_u64 v[146:147], v[150:151], 0, v[162:163]
	v_mov_b32_e32 v165, v73
	v_or_b32_e32 v164, 0x180, v72
	v_lshl_add_u64 v[166:167], v[150:151], 0, v[164:165]
	v_mfma_f32_16x16x32_bf16 v[28:31], v[116:119], v[108:111], v[28:31]
	v_or_b32_e32 v99, 16, v99
	s_add_i32 s43, s43, s33
	s_add_i32 s42, s42, s33
	v_mfma_f32_16x16x32_bf16 v[28:31], v[124:127], v[64:67], v[28:31]
	s_cmpk_gt_i32 s43, 0x7f
	s_waitcnt vmcnt(15)
	v_pk_mul_f32 v[62:63], v[62:63], v[174:175]
	v_pk_mul_f32 v[60:61], v[60:61], v[172:173]
	global_store_dwordx4 v[154:155], v[60:63], off
	v_lshl_add_u64 v[100:101], v[150:151], 0, v[156:157]
	v_mfma_f32_16x16x32_bf16 v[24:27], v[120:123], v[108:111], v[24:27]
	s_waitcnt vmcnt(15)
	v_pk_mul_f32 v[58:59], v[58:59], v[178:179]
	v_pk_mul_f32 v[56:57], v[56:57], v[176:177]
	global_store_dwordx4 v[154:155], v[56:59], off offset:16
	ds_read_b128 v[60:63], v145 offset:20480
	ds_read_b128 v[100:103], v168 offset:20480
	s_waitcnt lgkmcnt(1)
	v_mfma_f32_16x16x32_bf16 v[52:55], v[60:63], v[104:107], v[52:55]
	ds_read_b128 v[128:131], v145 offset:22528
	ds_read_b128 v[132:135], v168 offset:22528
	s_waitcnt lgkmcnt(2)
	v_mfma_f32_16x16x32_bf16 v[52:55], v[100:103], v[112:115], v[52:55]
	s_waitcnt lgkmcnt(1)
	v_mfma_f32_16x16x32_bf16 v[48:51], v[128:131], v[104:107], v[48:51]
	s_waitcnt vmcnt(15)
	s_nop 4
	v_pk_mul_f32 v[54:55], v[54:55], v[182:183]
	v_pk_mul_f32 v[52:53], v[52:53], v[180:181]
	global_store_dwordx4 v[154:155], v[52:55], off offset:128
	s_waitcnt lgkmcnt(0)
	v_mfma_f32_16x16x32_bf16 v[48:51], v[132:135], v[112:115], v[48:51]
	v_lshl_add_u64 v[56:57], v[150:151], 0, v[160:161]
	v_mfma_f32_16x16x32_bf16 v[24:27], v[68:71], v[64:67], v[24:27]
	v_mfma_f32_16x16x32_bf16 v[16:19], v[60:63], v[108:111], v[16:19]
	s_waitcnt vmcnt(15)
	s_nop 3
	v_pk_mul_f32 v[50:51], v[50:51], v[186:187]
	v_pk_mul_f32 v[48:49], v[48:49], v[184:185]
	global_store_dwordx4 v[154:155], v[48:51], off offset:144
	ds_read_b128 v[52:55], v145 offset:24576
	ds_read_b128 v[56:59], v168 offset:24576
	s_waitcnt lgkmcnt(1)
	v_mfma_f32_16x16x32_bf16 v[44:47], v[52:55], v[104:107], v[44:47]
	ds_read_b128 v[136:139], v145 offset:26624
	ds_read_b128 v[140:143], v168 offset:26624
	s_waitcnt lgkmcnt(2)
	v_mfma_f32_16x16x32_bf16 v[44:47], v[56:59], v[112:115], v[44:47]
	s_waitcnt lgkmcnt(1)
	v_mfma_f32_16x16x32_bf16 v[40:43], v[136:139], v[104:107], v[40:43]
	s_waitcnt vmcnt(15)
	s_nop 4
	v_pk_mul_f32 v[46:47], v[46:47], v[190:191]
	v_pk_mul_f32 v[44:45], v[44:45], v[188:189]
	global_store_dwordx4 v[154:155], v[44:47], off offset:256
	s_waitcnt lgkmcnt(0)
	v_mfma_f32_16x16x32_bf16 v[40:43], v[140:143], v[112:115], v[40:43]
	ds_read_b128 v[48:51], v145 offset:28672
	ds_read_b128 v[146:149], v145 offset:30720
	s_waitcnt lgkmcnt(1)
	v_mfma_f32_16x16x32_bf16 v[36:39], v[48:51], v[104:107], v[36:39]
	s_waitcnt vmcnt(15)
	s_nop 2
	v_pk_mul_f32 v[42:43], v[42:43], v[194:195]
	v_pk_mul_f32 v[40:41], v[40:41], v[192:193]
	global_store_dwordx4 v[154:155], v[40:43], off offset:272
	ds_read_b128 v[44:47], v168 offset:28672
	s_waitcnt lgkmcnt(1)
	v_mfma_f32_16x16x32_bf16 v[32:35], v[146:149], v[104:107], v[32:35]
	ds_read_b128 v[104:107], v168 offset:30720
	v_mov_b32_e32 v167, v73
	v_or_b32_e32 v166, 0x190, v72
	s_waitcnt lgkmcnt(1)
	v_mfma_f32_16x16x32_bf16 v[36:39], v[44:47], v[112:115], v[36:39]
	v_lshl_add_u64 v[116:117], v[150:151], 0, v[166:167]
	s_waitcnt vmcnt(15)
	s_nop 5
	v_pk_mul_f32 v[38:39], v[38:39], v[198:199]
	v_pk_mul_f32 v[36:37], v[36:37], v[196:197]
	global_store_dwordx4 v[154:155], v[36:39], off offset:384
	v_mul_hi_i32 v40, v99, s39
	v_lshrrev_b32_e32 v41, 31, v40
	v_ashrrev_i32_e32 v40, 11, v40
	v_add_u32_e32 v40, v40, v41
	v_mad_i32_i24 v41, v40, s40, v99
	v_cmp_lt_i32_e32 vcc, s41, v41
	s_waitcnt lgkmcnt(0)
	v_mfma_f32_16x16x32_bf16 v[32:35], v[104:107], v[112:115], v[32:35]
	v_cndmask_b32_e32 v40, 2, v40, vcc
	v_mul_hi_i32_i24_e32 v41, 0x6000, v40
	v_mul_i32_i24_e32 v40, 0x6000, v40
	v_lshl_add_u64 v[40:41], s[94:95], 0, v[40:41]
	v_lshl_add_u64 v[40:41], v[40:41], 0, s[34:35]
	v_lshl_add_u64 v[42:43], v[40:41], 0, v[72:73]
	v_mfma_f32_16x16x32_bf16 v[16:19], v[100:103], v[64:67], v[16:19]
	s_waitcnt vmcnt(15)
	v_pk_mul_f32 v[34:35], v[34:35], v[202:203]
	v_pk_mul_f32 v[32:33], v[32:33], v[200:201]
	global_store_dwordx4 v[154:155], v[32:35], off offset:400
	v_mul_hi_i32 v36, v99, s38
	v_lshrrev_b32_e32 v37, 31, v36
	v_lshrrev_b32_e32 v36, 11, v36
	v_add_u32_e32 v36, v36, v37
	v_lshl_add_u32 v36, v36, 13, v99
	v_ashrrev_i32_e32 v37, 31, v36
	v_lshl_add_u64 v[36:37], v[36:37], 0, s[8:9]
	v_lshlrev_b64 v[36:37], 12, v[36:37]
	v_lshl_add_u64 v[36:37], s[6:7], 0, v[36:37]
	v_lshl_add_u64 v[36:37], v[36:37], 0, v[72:73]
	v_lshl_add_u64 v[38:39], v[40:41], 0, v[152:153]
	v_mfma_f32_16x16x32_bf16 v[12:15], v[128:131], v[108:111], v[12:15]
	s_waitcnt vmcnt(15)
	v_pk_mul_f32 v[30:31], v[30:31], v[206:207]
	v_pk_mul_f32 v[28:29], v[28:29], v[204:205]
	global_store_dwordx4 v[36:37], v[28:31], off
	v_lshl_add_u64 v[32:33], v[40:41], 0, v[156:157]
	v_mfma_f32_16x16x32_bf16 v[12:15], v[132:135], v[64:67], v[12:15]
	s_waitcnt vmcnt(15)
	v_pk_mul_f32 v[26:27], v[26:27], v[210:211]
	v_pk_mul_f32 v[24:25], v[24:25], v[208:209]
	global_store_dwordx4 v[36:37], v[24:27], off offset:16
	v_lshl_add_u64 v[28:29], v[40:41], 0, v[158:159]
	v_mfma_f32_16x16x32_bf16 v[8:11], v[52:55], v[108:111], v[8:11]
	s_waitcnt vmcnt(15)
	v_pk_mul_f32 v[18:19], v[18:19], v[214:215]
	v_pk_mul_f32 v[16:17], v[16:17], v[212:213]
	global_store_dwordx4 v[36:37], v[16:19], off offset:128
	v_lshl_add_u64 v[24:25], v[40:41], 0, v[160:161]
	v_mfma_f32_16x16x32_bf16 v[8:11], v[56:59], v[64:67], v[8:11]
	s_waitcnt vmcnt(15)
	v_pk_mul_f32 v[14:15], v[14:15], v[218:219]
	v_pk_mul_f32 v[12:13], v[12:13], v[216:217]
	global_store_dwordx4 v[36:37], v[12:15], off offset:144
	v_lshl_add_u64 v[16:17], v[40:41], 0, v[162:163]
	v_mfma_f32_16x16x32_bf16 v[4:7], v[136:139], v[108:111], v[4:7]
	s_waitcnt vmcnt(15)
	v_pk_mul_f32 v[10:11], v[10:11], v[222:223]
	v_pk_mul_f32 v[8:9], v[8:9], v[220:221]
	global_store_dwordx4 v[36:37], v[8:11], off offset:256
	v_mfma_f32_16x16x32_bf16 v[4:7], v[140:143], v[64:67], v[4:7]
	v_lshl_add_u64 v[12:13], v[40:41], 0, v[164:165]
	v_mfma_f32_16x16x32_bf16 v[0:3], v[48:51], v[108:111], v[0:3]
	v_mfma_f32_16x16x32_bf16 v[0:3], v[44:47], v[64:67], v[0:3]
	s_waitcnt vmcnt(15)
	s_nop 3
	v_pk_mul_f32 v[6:7], v[6:7], v[226:227]
	v_pk_mul_f32 v[4:5], v[4:5], v[224:225]
	global_store_dwordx4 v[36:37], v[4:7], off offset:272
	v_lshl_add_u64 v[8:9], v[40:41], 0, v[166:167]
	v_mfma_f32_16x16x32_bf16 v[20:23], v[146:149], v[108:111], v[20:23]
	s_waitcnt vmcnt(15)
	v_pk_mul_f32 v[2:3], v[2:3], v[230:231]
	v_pk_mul_f32 v[0:1], v[0:1], v[228:229]
	global_store_dwordx4 v[36:37], v[0:3], off offset:384
	v_mfma_f32_16x16x32_bf16 v[4:7], v[104:107], v[64:67], v[20:23]
	s_waitcnt vmcnt(15)
	s_nop 6
	v_pk_mul_f32 v[234:235], v[6:7], v[234:235]
	v_pk_mul_f32 v[232:233], v[4:5], v[232:233]
	global_store_dwordx4 v[36:37], v[232:235], off offset:400
	s_cbranch_scc0 .LBB0_1090

.LBB0_1217:
	s_add_i32 s41, s3, 0x8000
	s_and_b32 s40, s41, 0x8000
	s_add_i32 s40, s40, 0
	s_add_u32 s86, s40, s87
	s_mov_b32 m0, s86
	s_waitcnt vmcnt(0) lgkmcnt(0)
	s_barrier
	global_load_lds_dwordx4 v244, s[96:97]
	s_add_u32 m0, s86, 0x4000
	s_nop 0
	global_load_lds_dwordx4 v245, s[88:89]
	s_add_u32 m0, s86, 0x1000
	s_nop 0
	global_load_lds_dwordx4 v246, s[96:97]
	s_add_u32 m0, s86, 0x5000
	s_nop 0
	global_load_lds_dwordx4 v247, s[88:89]
	s_add_u32 m0, s86, 0x2000
	s_nop 0
	global_load_lds_dwordx4 v248, s[96:97]
	s_add_u32 m0, s86, 0x6000
	s_nop 0
	global_load_lds_dwordx4 v249, s[88:89]
	s_add_u32 m0, s86, 0x3000
	s_nop 0
	global_load_lds_dwordx4 v250, s[96:97]
	s_add_u32 m0, s86, 0x7000
	s_nop 0
	global_load_lds_dwordx4 v251, s[88:89]
	s_add_u32 s96, s96, 0x80
	s_addc_u32 s97, s97, 0
	s_add_u32 s88, s88, 0x80
	s_addc_u32 s89, s89, 0
	s_and_b32 s3, s3, 0x8000
	s_add_i32 s3, s3, 0
	v_add3_u32 v145, s3, v87, v88
	v_add3_u32 v186, s3, v88, v89
	v_add3_u32 v187, s3, v87, v90
	v_add3_u32 v188, s3, v89, v90
	ds_read_b128 v[112:115], v186
	ds_read_b128 v[104:107], v145 offset:16384
	ds_read_b128 v[108:111], v145 offset:18432
	ds_read_b128 v[116:119], v186 offset:2048
	ds_read_b128 v[120:123], v145 offset:20480
	ds_read_b128 v[124:127], v145 offset:22528
	ds_read_b128 v[128:131], v145 offset:24576
	ds_read_b128 v[132:135], v145 offset:26624
	ds_read_b128 v[136:139], v145 offset:28672
	ds_read_b128 v[140:143], v145 offset:30720
	ds_read_b128 v[154:157], v188
	ds_read_b128 v[146:149], v187 offset:16384
	ds_read_b128 v[150:153], v187 offset:18432
	ds_read_b128 v[158:161], v188 offset:2048
	ds_read_b128 v[162:165], v187 offset:20480
	ds_read_b128 v[166:169], v187 offset:22528
	ds_read_b128 v[170:173], v187 offset:24576
	ds_read_b128 v[174:177], v187 offset:26624
	ds_read_b128 v[178:181], v187 offset:28672
	ds_read_b128 v[182:185], v187 offset:30720
	s_add_u32 s0, s0, 0x80
	s_addc_u32 s1, s1, 0
	s_cmpk_eq_i32 s0, 0x780
	s_mov_b32 s3, s41
	s_waitcnt lgkmcnt(15)
	v_mfma_f32_16x16x32_bf16 v[60:63], v[104:107], v[112:115], v[60:63]
	v_mfma_f32_16x16x32_bf16 v[56:59], v[108:111], v[112:115], v[56:59]
	v_mfma_f32_16x16x32_bf16 v[24:27], v[104:107], v[116:119], v[24:27]
	v_mfma_f32_16x16x32_bf16 v[20:23], v[108:111], v[116:119], v[20:23]
	v_mfma_f32_16x16x32_bf16 v[16:19], v[120:123], v[116:119], v[16:19]
	v_mfma_f32_16x16x32_bf16 v[52:55], v[120:123], v[112:115], v[52:55]
	s_waitcnt lgkmcnt(14)
	v_mfma_f32_16x16x32_bf16 v[48:51], v[124:127], v[112:115], v[48:51]
	v_mfma_f32_16x16x32_bf16 v[12:15], v[124:127], v[116:119], v[12:15]
	s_waitcnt lgkmcnt(13)
	v_mfma_f32_16x16x32_bf16 v[8:11], v[128:131], v[116:119], v[8:11]
	v_mfma_f32_16x16x32_bf16 v[44:47], v[128:131], v[112:115], v[44:47]
	s_waitcnt lgkmcnt(12)
	v_mfma_f32_16x16x32_bf16 v[36:39], v[132:135], v[112:115], v[36:39]
	v_mfma_f32_16x16x32_bf16 v[4:7], v[132:135], v[116:119], v[4:7]
	s_waitcnt lgkmcnt(11)
	v_mfma_f32_16x16x32_bf16 v[0:3], v[136:139], v[116:119], v[0:3]
	v_mfma_f32_16x16x32_bf16 v[32:35], v[136:139], v[112:115], v[32:35]
	s_waitcnt lgkmcnt(10)
	v_mfma_f32_16x16x32_bf16 v[28:31], v[140:143], v[112:115], v[28:31]
	v_mfma_f32_16x16x32_bf16 v[40:43], v[140:143], v[116:119], v[40:43]
	s_waitcnt lgkmcnt(8)
	v_mfma_f32_16x16x32_bf16 v[60:63], v[146:149], v[154:157], v[60:63]
	s_waitcnt lgkmcnt(7)
	v_mfma_f32_16x16x32_bf16 v[56:59], v[150:153], v[154:157], v[56:59]
	s_waitcnt lgkmcnt(6)
	v_mfma_f32_16x16x32_bf16 v[24:27], v[146:149], v[158:161], v[24:27]
	v_mfma_f32_16x16x32_bf16 v[20:23], v[150:153], v[158:161], v[20:23]
	s_waitcnt lgkmcnt(5)
	v_mfma_f32_16x16x32_bf16 v[16:19], v[162:165], v[158:161], v[16:19]
	v_mfma_f32_16x16x32_bf16 v[52:55], v[162:165], v[154:157], v[52:55]
	s_waitcnt lgkmcnt(4)
	v_mfma_f32_16x16x32_bf16 v[48:51], v[166:169], v[154:157], v[48:51]
	v_mfma_f32_16x16x32_bf16 v[12:15], v[166:169], v[158:161], v[12:15]
	s_waitcnt lgkmcnt(3)
	v_mfma_f32_16x16x32_bf16 v[8:11], v[170:173], v[158:161], v[8:11]
	v_mfma_f32_16x16x32_bf16 v[44:47], v[170:173], v[154:157], v[44:47]
	s_waitcnt lgkmcnt(2)
	v_mfma_f32_16x16x32_bf16 v[36:39], v[174:177], v[154:157], v[36:39]
	v_mfma_f32_16x16x32_bf16 v[4:7], v[174:177], v[158:161], v[4:7]
	s_waitcnt lgkmcnt(1)
	v_mfma_f32_16x16x32_bf16 v[0:3], v[178:181], v[158:161], v[0:3]
	v_mfma_f32_16x16x32_bf16 v[32:35], v[178:181], v[154:157], v[32:35]
	s_waitcnt lgkmcnt(0)
	v_mfma_f32_16x16x32_bf16 v[28:31], v[182:185], v[154:157], v[28:31]
	v_mfma_f32_16x16x32_bf16 v[40:43], v[182:185], v[158:161], v[40:43]
	s_cbranch_scc0 .LBB0_1217
	v_add_u32_e32 v64, s40, v87
	v_add_u32_e32 v103, v64, v88
	v_add3_u32 v112, s40, v88, v89
	s_waitcnt vmcnt(0)
	s_barrier
	ds_read_b128 v[82:85], v103 offset:16384
	ds_read_b128 v[104:107], v103 offset:18432
	ds_read_b128 v[108:111], v112
	ds_read_b128 v[112:115], v112 offset:2048
	ds_read_b128 v[116:119], v103 offset:20480
	ds_read_b128 v[120:123], v103 offset:22528
	ds_read_b128 v[124:127], v103 offset:24576
	ds_read_b128 v[128:131], v103 offset:26624
	ds_read_b128 v[132:135], v103 offset:28672
	ds_read_b128 v[136:139], v103 offset:30720
	v_add_u32_e32 v64, v64, v90
	s_waitcnt lgkmcnt(7)
	v_mfma_f32_16x16x32_bf16 v[60:63], v[82:85], v[108:111], v[60:63]
	s_mul_hi_i32 s0, s2, 0x3e0f83e1
	s_lshr_b32 s1, s0, 31
	s_ashr_i32 s56, s0, 4
	v_mfma_f32_16x16x32_bf16 v[56:59], v[104:107], v[108:111], v[56:59]
	s_add_i32 s56, s56, s1
	s_cmp_gt_i32 s39, 11
	s_cselect_b64 s[0:1], -1, 0
	s_waitcnt lgkmcnt(4)
	v_mfma_f32_16x16x32_bf16 v[48:51], v[120:123], v[108:111], v[48:51]
	s_lshl_b32 s53, s2, 7
	s_cmp_lt_i32 s39, 12
	s_mul_i32 s54, s56, 0xffffdf00
	s_waitcnt lgkmcnt(3)
	v_mfma_f32_16x16x32_bf16 v[44:47], v[124:127], v[108:111], v[44:47]
	s_waitcnt lgkmcnt(2)
	v_mfma_f32_16x16x32_bf16 v[36:39], v[128:131], v[108:111], v[36:39]
	s_waitcnt lgkmcnt(1)
	v_mfma_f32_16x16x32_bf16 v[32:35], v[132:135], v[108:111], v[32:35]
	s_waitcnt lgkmcnt(0)
	v_mfma_f32_16x16x32_bf16 v[28:31], v[136:139], v[108:111], v[28:31]
	v_mfma_f32_16x16x32_bf16 v[24:27], v[82:85], v[112:115], v[24:27]
	ds_read_b128 v[82:85], v64 offset:16384
	v_mfma_f32_16x16x32_bf16 v[52:55], v[116:119], v[108:111], v[52:55]
	v_mfma_f32_16x16x32_bf16 v[20:23], v[104:107], v[112:115], v[20:23]
	v_mfma_f32_16x16x32_bf16 v[16:19], v[116:119], v[112:115], v[16:19]
	v_mfma_f32_16x16x32_bf16 v[12:15], v[120:123], v[112:115], v[12:15]
	v_mfma_f32_16x16x32_bf16 v[8:11], v[124:127], v[112:115], v[8:11]
	v_mfma_f32_16x16x32_bf16 v[4:7], v[128:131], v[112:115], v[4:7]
	v_mfma_f32_16x16x32_bf16 v[0:3], v[132:135], v[112:115], v[0:3]
	v_mfma_f32_16x16x32_bf16 v[104:107], v[136:139], v[112:115], v[40:43]
	s_nop 2
	v_add3_u32 v40, s40, v90, v89
	ds_read_b128 v[108:111], v64 offset:18432
	ds_read_b128 v[112:115], v40
	ds_read_b128 v[116:119], v40 offset:2048
	ds_read_b128 v[120:123], v64 offset:20480
	ds_read_b128 v[124:127], v64 offset:22528
	ds_read_b128 v[128:131], v64 offset:24576
	ds_read_b128 v[132:135], v64 offset:26624
	ds_read_b128 v[136:139], v64 offset:28672
	ds_read_b128 v[140:143], v64 offset:30720
	s_waitcnt lgkmcnt(7)
	v_mfma_f32_16x16x32_bf16 v[60:63], v[82:85], v[112:115], v[60:63]
	v_mfma_f32_16x16x32_bf16 v[56:59], v[108:111], v[112:115], v[56:59]
	s_waitcnt lgkmcnt(5)
	v_mfma_f32_16x16x32_bf16 v[52:55], v[120:123], v[112:115], v[52:55]
	s_waitcnt lgkmcnt(4)
	v_mfma_f32_16x16x32_bf16 v[48:51], v[124:127], v[112:115], v[48:51]
	s_waitcnt lgkmcnt(3)
	v_mfma_f32_16x16x32_bf16 v[44:47], v[128:131], v[112:115], v[44:47]
	s_waitcnt lgkmcnt(2)
	v_mfma_f32_16x16x32_bf16 v[40:43], v[132:135], v[112:115], v[36:39]
	s_waitcnt lgkmcnt(1)
	v_mfma_f32_16x16x32_bf16 v[36:39], v[136:139], v[112:115], v[32:35]
	s_waitcnt lgkmcnt(0)
	v_mfma_f32_16x16x32_bf16 v[32:35], v[140:143], v[112:115], v[28:31]
	v_mfma_f32_16x16x32_bf16 v[28:31], v[82:85], v[116:119], v[24:27]
	v_mfma_f32_16x16x32_bf16 v[24:27], v[108:111], v[116:119], v[20:23]
	v_mfma_f32_16x16x32_bf16 v[20:23], v[120:123], v[116:119], v[16:19]
	v_mfma_f32_16x16x32_bf16 v[16:19], v[124:127], v[116:119], v[12:15]
	v_mfma_f32_16x16x32_bf16 v[12:15], v[128:131], v[116:119], v[8:11]
	v_mfma_f32_16x16x32_bf16 v[8:11], v[132:135], v[116:119], v[4:7]
	v_mfma_f32_16x16x32_bf16 v[4:7], v[136:139], v[116:119], v[0:3]
	v_mfma_f32_16x16x32_bf16 v[0:3], v[140:143], v[116:119], v[104:107]
	s_cbranch_scc0 .LBB0_1224
	s_add_i32 s40, s54, s53
	v_add_u32_e32 v64, s40, v70
	v_cmp_lt_i32_e32 vcc, s48, v64
	s_and_saveexec_b64 s[2:3], vcc
	s_cbranch_execz .LBB0_1221
	v_lshl_add_u32 v64, v64, 5, v102
	v_lshlrev_b64 v[108:109], 2, v[64:65]
	v_lshl_add_u64 v[104:105], v[76:77], 0, v[108:109]
	global_load_dwordx4 v[82:85], v[104:105], off
	s_nop 0
	global_load_dwordx4 v[104:107], v[104:105], off offset:16
	v_lshl_add_u64 v[112:113], v[74:75], 0, v[108:109]
	global_load_dwordx4 v[108:111], v[112:113], off
	s_nop 0
	global_load_dwordx4 v[112:115], v[112:113], off offset:16
	s_waitcnt vmcnt(3)
	v_pk_mul_f32 v[116:117], v[54:55], v[84:85]
	v_pk_mul_f32 v[118:119], v[52:53], v[82:83]
	v_pk_mul_f32 v[120:121], v[62:63], v[84:85]
	v_pk_mul_f32 v[122:123], v[60:61], v[82:83]
	s_waitcnt vmcnt(2)
	v_pk_mul_f32 v[124:125], v[50:51], v[106:107]
	v_pk_mul_f32 v[126:127], v[48:49], v[104:105]
	v_pk_mul_f32 v[128:129], v[58:59], v[106:107]
	v_pk_mul_f32 v[130:131], v[56:57], v[104:105]
	v_pk_mul_f32 v[132:133], v[38:39], v[84:85]
	v_pk_mul_f32 v[134:135], v[36:37], v[82:83]
	v_pk_mul_f32 v[84:85], v[46:47], v[84:85]
	v_pk_mul_f32 v[82:83], v[44:45], v[82:83]
	v_pk_mul_f32 v[136:137], v[34:35], v[106:107]
	v_pk_mul_f32 v[138:139], v[32:33], v[104:105]
	v_pk_mul_f32 v[106:107], v[42:43], v[106:107]
	v_pk_mul_f32 v[104:105], v[40:41], v[104:105]
	s_waitcnt vmcnt(1)
	v_pk_fma_f32 v[62:63], v[62:63], v[110:111], v[116:117] neg_lo:[0,0,1] neg_hi:[0,0,1]
	v_pk_fma_f32 v[60:61], v[60:61], v[108:109], v[118:119] neg_lo:[0,0,1] neg_hi:[0,0,1]
	v_pk_fma_f32 v[54:55], v[54:55], v[110:111], v[120:121]
	v_pk_fma_f32 v[52:53], v[52:53], v[108:109], v[122:123]
	s_waitcnt vmcnt(0)
	v_pk_fma_f32 v[58:59], v[58:59], v[114:115], v[124:125] neg_lo:[0,0,1] neg_hi:[0,0,1]
	v_pk_fma_f32 v[56:57], v[56:57], v[112:113], v[126:127] neg_lo:[0,0,1] neg_hi:[0,0,1]
	v_pk_fma_f32 v[50:51], v[50:51], v[114:115], v[128:129]
	v_pk_fma_f32 v[48:49], v[48:49], v[112:113], v[130:131]
	v_pk_fma_f32 v[46:47], v[46:47], v[110:111], v[132:133] neg_lo:[0,0,1] neg_hi:[0,0,1]
	v_pk_fma_f32 v[44:45], v[44:45], v[108:109], v[134:135] neg_lo:[0,0,1] neg_hi:[0,0,1]
	v_pk_fma_f32 v[38:39], v[38:39], v[110:111], v[84:85]
	v_pk_fma_f32 v[36:37], v[36:37], v[108:109], v[82:83]
	v_pk_fma_f32 v[42:43], v[42:43], v[114:115], v[136:137] neg_lo:[0,0,1] neg_hi:[0,0,1]
	v_pk_fma_f32 v[40:41], v[40:41], v[112:113], v[138:139] neg_lo:[0,0,1] neg_hi:[0,0,1]
	v_pk_fma_f32 v[34:35], v[34:35], v[114:115], v[106:107]
	v_pk_fma_f32 v[32:33], v[32:33], v[112:113], v[104:105]

.LBB0_1615:
	s_add_i32 s41, s39, 0x8000
	s_and_b32 s40, s41, 0x8000
	s_add_i32 s40, s40, 0
	s_add_u32 s86, s40, s87
	s_mov_b32 m0, s86
	s_waitcnt vmcnt(0) lgkmcnt(0)
	s_barrier
	global_load_lds_dwordx4 v244, s[96:97]
	s_add_u32 m0, s86, 0x4000
	s_nop 0
	global_load_lds_dwordx4 v245, s[88:89]
	s_add_u32 m0, s86, 0x1000
	s_nop 0
	global_load_lds_dwordx4 v246, s[96:97]
	s_add_u32 m0, s86, 0x5000
	s_nop 0
	global_load_lds_dwordx4 v247, s[88:89]
	s_add_u32 m0, s86, 0x2000
	s_nop 0
	global_load_lds_dwordx4 v248, s[96:97]
	s_add_u32 m0, s86, 0x6000
	s_nop 0
	global_load_lds_dwordx4 v249, s[88:89]
	s_add_u32 m0, s86, 0x3000
	s_nop 0
	global_load_lds_dwordx4 v250, s[96:97]
	s_add_u32 m0, s86, 0x7000
	s_nop 0
	global_load_lds_dwordx4 v251, s[88:89]
	s_add_u32 s96, s96, 0x80
	s_addc_u32 s97, s97, 0
	s_add_u32 s88, s88, 0x80
	s_addc_u32 s89, s89, 0
	s_and_b32 s39, s39, 0x8000
	s_add_i32 s39, s39, 0
	v_add3_u32 v145, s39, v84, v85
	v_add3_u32 v178, s39, v85, v86
	v_add3_u32 v179, s39, v84, v87
	v_add3_u32 v180, s39, v86, v87
	ds_read_b128 v[104:107], v178
	ds_read_b128 v[76:79], v145 offset:16384
	ds_read_b128 v[100:103], v145 offset:18432
	ds_read_b128 v[108:111], v178 offset:2048
	ds_read_b128 v[112:115], v145 offset:20480
	ds_read_b128 v[116:119], v145 offset:22528
	ds_read_b128 v[120:123], v145 offset:24576
	ds_read_b128 v[124:127], v145 offset:26624
	ds_read_b128 v[128:131], v145 offset:28672
	ds_read_b128 v[132:135], v145 offset:30720
	ds_read_b128 v[146:149], v180
	ds_read_b128 v[136:139], v179 offset:16384
	ds_read_b128 v[140:143], v179 offset:18432
	ds_read_b128 v[150:153], v180 offset:2048
	ds_read_b128 v[154:157], v179 offset:20480
	ds_read_b128 v[158:161], v179 offset:22528
	ds_read_b128 v[162:165], v179 offset:24576
	ds_read_b128 v[166:169], v179 offset:26624
	ds_read_b128 v[170:173], v179 offset:28672
	ds_read_b128 v[174:177], v179 offset:30720
	s_add_u32 s28, s28, 0x80
	s_addc_u32 s29, s29, 0
	s_cmpk_eq_i32 s28, 0x780
	s_mov_b32 s39, s41
	s_waitcnt lgkmcnt(15)
	v_mfma_f32_16x16x32_bf16 v[60:63], v[76:79], v[104:107], v[60:63]
	v_mfma_f32_16x16x32_bf16 v[56:59], v[100:103], v[104:107], v[56:59]
	v_mfma_f32_16x16x32_bf16 v[24:27], v[76:79], v[108:111], v[24:27]
	v_mfma_f32_16x16x32_bf16 v[20:23], v[100:103], v[108:111], v[20:23]
	v_mfma_f32_16x16x32_bf16 v[16:19], v[112:115], v[108:111], v[16:19]
	v_mfma_f32_16x16x32_bf16 v[52:55], v[112:115], v[104:107], v[52:55]
	s_waitcnt lgkmcnt(14)
	v_mfma_f32_16x16x32_bf16 v[48:51], v[116:119], v[104:107], v[48:51]
	v_mfma_f32_16x16x32_bf16 v[12:15], v[116:119], v[108:111], v[12:15]
	s_waitcnt lgkmcnt(13)
	v_mfma_f32_16x16x32_bf16 v[8:11], v[120:123], v[108:111], v[8:11]
	v_mfma_f32_16x16x32_bf16 v[44:47], v[120:123], v[104:107], v[44:47]
	s_waitcnt lgkmcnt(12)
	v_mfma_f32_16x16x32_bf16 v[40:43], v[124:127], v[104:107], v[40:43]
	v_mfma_f32_16x16x32_bf16 v[4:7], v[124:127], v[108:111], v[4:7]
	s_waitcnt lgkmcnt(11)
	v_mfma_f32_16x16x32_bf16 v[0:3], v[128:131], v[108:111], v[0:3]
	v_mfma_f32_16x16x32_bf16 v[32:35], v[128:131], v[104:107], v[32:35]
	s_waitcnt lgkmcnt(10)
	v_mfma_f32_16x16x32_bf16 v[28:31], v[132:135], v[104:107], v[28:31]
	v_mfma_f32_16x16x32_bf16 v[36:39], v[132:135], v[108:111], v[36:39]
	s_waitcnt lgkmcnt(8)
	v_mfma_f32_16x16x32_bf16 v[60:63], v[136:139], v[146:149], v[60:63]
	s_waitcnt lgkmcnt(7)
	v_mfma_f32_16x16x32_bf16 v[56:59], v[140:143], v[146:149], v[56:59]
	s_waitcnt lgkmcnt(6)
	v_mfma_f32_16x16x32_bf16 v[24:27], v[136:139], v[150:153], v[24:27]
	v_mfma_f32_16x16x32_bf16 v[20:23], v[140:143], v[150:153], v[20:23]
	s_waitcnt lgkmcnt(5)
	v_mfma_f32_16x16x32_bf16 v[16:19], v[154:157], v[150:153], v[16:19]
	v_mfma_f32_16x16x32_bf16 v[52:55], v[154:157], v[146:149], v[52:55]
	s_waitcnt lgkmcnt(4)
	v_mfma_f32_16x16x32_bf16 v[48:51], v[158:161], v[146:149], v[48:51]
	v_mfma_f32_16x16x32_bf16 v[12:15], v[158:161], v[150:153], v[12:15]
	s_waitcnt lgkmcnt(3)
	v_mfma_f32_16x16x32_bf16 v[8:11], v[162:165], v[150:153], v[8:11]
	v_mfma_f32_16x16x32_bf16 v[44:47], v[162:165], v[146:149], v[44:47]
	s_waitcnt lgkmcnt(2)
	v_mfma_f32_16x16x32_bf16 v[40:43], v[166:169], v[146:149], v[40:43]
	v_mfma_f32_16x16x32_bf16 v[4:7], v[166:169], v[150:153], v[4:7]
	s_waitcnt lgkmcnt(1)
	v_mfma_f32_16x16x32_bf16 v[0:3], v[170:173], v[150:153], v[0:3]
	v_mfma_f32_16x16x32_bf16 v[32:35], v[170:173], v[146:149], v[32:35]
	s_waitcnt lgkmcnt(0)
	v_mfma_f32_16x16x32_bf16 v[28:31], v[174:177], v[146:149], v[28:31]
	v_mfma_f32_16x16x32_bf16 v[36:39], v[174:177], v[150:153], v[36:39]
	s_cbranch_scc0 .LBB0_1615
	v_add_u32_e32 v80, s40, v84
	v_add_u32_e32 v81, v80, v85
	s_waitcnt vmcnt(0)
	s_barrier
	ds_read_b128 v[72:75], v81 offset:16384
	v_add3_u32 v99, s40, v85, v86
	ds_read_b128 v[76:79], v81 offset:18432
	ds_read_b128 v[100:103], v99
	ds_read_b128 v[104:107], v99 offset:2048
	ds_read_b128 v[108:111], v81 offset:20480
	ds_read_b128 v[112:115], v81 offset:22528
	ds_read_b128 v[116:119], v81 offset:24576
	ds_read_b128 v[120:123], v81 offset:26624
	ds_read_b128 v[124:127], v81 offset:28672
	ds_read_b128 v[128:131], v81 offset:30720
	v_add_u32_e32 v80, v80, v87
	s_waitcnt lgkmcnt(7)
	v_mfma_f32_16x16x32_bf16 v[60:63], v[72:75], v[100:103], v[60:63]
	s_lshl_b32 s38, s38, 7
	v_mfma_f32_16x16x32_bf16 v[56:59], v[76:79], v[100:103], v[56:59]
	s_waitcnt lgkmcnt(4)
	v_mfma_f32_16x16x32_bf16 v[48:51], v[112:115], v[100:103], v[48:51]
	s_waitcnt lgkmcnt(3)
	v_mfma_f32_16x16x32_bf16 v[44:47], v[116:119], v[100:103], v[44:47]
	s_waitcnt lgkmcnt(2)
	v_mfma_f32_16x16x32_bf16 v[40:43], v[120:123], v[100:103], v[40:43]
	s_waitcnt lgkmcnt(1)
	v_mfma_f32_16x16x32_bf16 v[32:35], v[124:127], v[100:103], v[32:35]
	s_waitcnt lgkmcnt(0)
	v_mfma_f32_16x16x32_bf16 v[28:31], v[128:131], v[100:103], v[28:31]
	v_mfma_f32_16x16x32_bf16 v[24:27], v[72:75], v[104:107], v[24:27]
	ds_read_b128 v[72:75], v80 offset:16384
	v_mfma_f32_16x16x32_bf16 v[52:55], v[108:111], v[100:103], v[52:55]
	v_mfma_f32_16x16x32_bf16 v[20:23], v[76:79], v[104:107], v[20:23]
	v_mfma_f32_16x16x32_bf16 v[16:19], v[108:111], v[104:107], v[16:19]
	v_mfma_f32_16x16x32_bf16 v[12:15], v[112:115], v[104:107], v[12:15]
	v_mfma_f32_16x16x32_bf16 v[8:11], v[116:119], v[104:107], v[8:11]
	v_mfma_f32_16x16x32_bf16 v[4:7], v[120:123], v[104:107], v[4:7]
	v_mfma_f32_16x16x32_bf16 v[0:3], v[124:127], v[104:107], v[0:3]
	v_mfma_f32_16x16x32_bf16 v[100:103], v[128:131], v[104:107], v[36:39]
	s_nop 2
	v_add3_u32 v36, s40, v87, v86
	ds_read_b128 v[76:79], v80 offset:18432
	ds_read_b128 v[104:107], v36
	ds_read_b128 v[108:111], v36 offset:2048
	ds_read_b128 v[128:131], v80 offset:28672
	ds_read_b128 v[132:135], v80 offset:30720
	ds_read_b128 v[112:115], v80 offset:20480
	ds_read_b128 v[116:119], v80 offset:22528
	ds_read_b128 v[120:123], v80 offset:24576
	ds_read_b128 v[124:127], v80 offset:26624
	s_waitcnt lgkmcnt(7)
	v_mfma_f32_16x16x32_bf16 v[60:63], v[72:75], v[104:107], v[60:63]
	s_waitcnt lgkmcnt(5)
	v_mfma_f32_16x16x32_bf16 v[36:39], v[128:131], v[104:107], v[32:35]
	s_waitcnt lgkmcnt(4)
	v_mfma_f32_16x16x32_bf16 v[32:35], v[132:135], v[104:107], v[28:31]
	v_mfma_f32_16x16x32_bf16 v[28:31], v[72:75], v[108:111], v[24:27]
	v_add_u32_e32 v72, s38, v83
	v_mul_hi_i32 v73, v72, s31
	v_mfma_f32_16x16x32_bf16 v[24:27], v[76:79], v[108:111], v[20:23]
	s_waitcnt lgkmcnt(3)
	v_mfma_f32_16x16x32_bf16 v[20:23], v[112:115], v[108:111], v[16:19]
	s_waitcnt lgkmcnt(2)
	v_mfma_f32_16x16x32_bf16 v[16:19], v[116:119], v[108:111], v[12:15]
	s_waitcnt lgkmcnt(1)
	v_mfma_f32_16x16x32_bf16 v[12:15], v[120:123], v[108:111], v[8:11]
	s_waitcnt lgkmcnt(0)
	v_mfma_f32_16x16x32_bf16 v[8:11], v[124:127], v[108:111], v[4:7]
	s_nop 2
	v_lshrrev_b32_e32 v4, 31, v73
	v_ashrrev_i32_e32 v5, 11, v73
	v_mfma_f32_16x16x32_bf16 v[56:59], v[76:79], v[104:107], v[56:59]
	v_add_u32_e32 v73, v5, v4
	v_mad_i32_i24 v78, v73, s33, v72
	v_lshlrev_b32_e32 v75, 13, v73
	v_mfma_f32_16x16x32_bf16 v[52:55], v[112:115], v[104:107], v[52:55]
	v_cmp_lt_i32_e32 vcc, s34, v78
	v_add3_u32 v74, v75, v78, s35
	v_mfma_f32_16x16x32_bf16 v[48:51], v[116:119], v[104:107], v[48:51]
	v_mfma_f32_16x16x32_bf16 v[44:47], v[120:123], v[104:107], v[44:47]
	v_mfma_f32_16x16x32_bf16 v[40:43], v[124:127], v[104:107], v[40:43]
	v_mfma_f32_16x16x32_bf16 v[4:7], v[128:131], v[108:111], v[0:3]
	v_mfma_f32_16x16x32_bf16 v[0:3], v[132:135], v[108:111], v[100:103]
	s_and_saveexec_b64 s[28:29], vcc
	s_xor_b64 s[28:29], exec, s[28:29]
	v_add3_u32 v72, v75, v78, s35
	s_or_saveexec_b64 s[28:29], s[28:29]
	v_mov_b64_e32 v[76:77], s[92:93]
	v_lshl_add_u32 v75, v73, 8, v78
	s_xor_b64 exec, exec, s[28:29]
	v_lshl_add_u32 v72, v73, 8, v78
	v_mov_b64_e32 v[76:77], s[2:3]
	s_or_b64 exec, exec, s[28:29]
	s_and_saveexec_b64 s[28:29], vcc
	s_xor_b64 s[28:29], exec, s[28:29]
	s_cbranch_execz .LBB0_1622
	v_add_u32_e32 v73, 3, v73
	v_mul_hi_i32_i24_e32 v79, 0x6000, v73
	v_mul_i32_i24_e32 v78, 0x6000, v73
	s_or_saveexec_b64 s[28:29], s[28:29]
	v_mov_b64_e32 v[80:81], s[92:93]
	s_xor_b64 exec, exec, s[28:29]
	s_cbranch_execnz .LBB0_1623
	s_branch .LBB0_1624

.LBB0_1759:
	s_add_i32 s36, s34, 0x8000
	s_and_b32 s35, s36, 0x8000
	s_add_i32 s35, s35, 0
	s_add_u32 s86, s35, s87
	s_mov_b32 m0, s86
	s_waitcnt vmcnt(0) lgkmcnt(0)
	s_barrier
	global_load_lds_dwordx4 v244, s[96:97]
	s_add_u32 m0, s86, 0x4000
	s_nop 0
	global_load_lds_dwordx4 v245, s[88:89]
	s_add_u32 m0, s86, 0x1000
	s_nop 0
	global_load_lds_dwordx4 v246, s[96:97]
	s_add_u32 m0, s86, 0x5000
	s_nop 0
	global_load_lds_dwordx4 v247, s[88:89]
	s_add_u32 m0, s86, 0x2000
	s_nop 0
	global_load_lds_dwordx4 v248, s[96:97]
	s_add_u32 m0, s86, 0x6000
	s_nop 0
	global_load_lds_dwordx4 v249, s[88:89]
	s_add_u32 m0, s86, 0x3000
	s_nop 0
	global_load_lds_dwordx4 v250, s[96:97]
	s_add_u32 m0, s86, 0x7000
	s_nop 0
	global_load_lds_dwordx4 v251, s[88:89]
	s_add_u32 s96, s96, 0x80
	s_addc_u32 s97, s97, 0
	s_add_u32 s88, s88, 0x80
	s_addc_u32 s89, s89, 0
	s_and_b32 s34, s34, 0x8000
	s_add_i32 s34, s34, 0
	v_add3_u32 v143, s34, v80, v81
	v_add3_u32 v145, s34, v81, v82
	v_add3_u32 v206, s34, v80, v83
	v_add3_u32 v207, s34, v82, v83
	ds_read_b128 v[102:105], v145
	ds_read_b128 v[94:97], v143 offset:16384
	ds_read_b128 v[98:101], v143 offset:18432
	ds_read_b128 v[106:109], v145 offset:2048
	ds_read_b128 v[110:113], v143 offset:20480
	ds_read_b128 v[114:117], v143 offset:22528
	ds_read_b128 v[118:121], v143 offset:24576
	ds_read_b128 v[122:125], v143 offset:26624
	ds_read_b128 v[126:129], v143 offset:28672
	ds_read_b128 v[130:133], v143 offset:30720
	ds_read_b128 v[174:177], v207
	ds_read_b128 v[166:169], v206 offset:16384
	ds_read_b128 v[170:173], v206 offset:18432
	ds_read_b128 v[178:181], v207 offset:2048
	ds_read_b128 v[182:185], v206 offset:20480
	ds_read_b128 v[186:189], v206 offset:22528
	ds_read_b128 v[190:193], v206 offset:24576
	ds_read_b128 v[194:197], v206 offset:26624
	ds_read_b128 v[198:201], v206 offset:28672
	ds_read_b128 v[202:205], v206 offset:30720
	s_add_u32 s26, s26, 0x80
	s_addc_u32 s27, s27, 0
	s_cmpk_eq_i32 s26, 0x780
	s_mov_b32 s34, s36
	s_waitcnt lgkmcnt(15)
	v_mfma_f32_16x16x32_bf16 v[60:63], v[94:97], v[102:105], v[60:63]
	v_mfma_f32_16x16x32_bf16 v[56:59], v[98:101], v[102:105], v[56:59]
	v_mfma_f32_16x16x32_bf16 v[28:31], v[94:97], v[106:109], v[28:31]
	v_mfma_f32_16x16x32_bf16 v[24:27], v[98:101], v[106:109], v[24:27]
	v_mfma_f32_16x16x32_bf16 v[20:23], v[110:113], v[106:109], v[20:23]
	v_mfma_f32_16x16x32_bf16 v[52:55], v[110:113], v[102:105], v[52:55]
	s_waitcnt lgkmcnt(14)
	v_mfma_f32_16x16x32_bf16 v[48:51], v[114:117], v[102:105], v[48:51]
	v_mfma_f32_16x16x32_bf16 v[12:15], v[114:117], v[106:109], v[12:15]
	s_waitcnt lgkmcnt(13)
	v_mfma_f32_16x16x32_bf16 v[8:11], v[118:121], v[106:109], v[8:11]
	v_mfma_f32_16x16x32_bf16 v[44:47], v[118:121], v[102:105], v[44:47]
	s_waitcnt lgkmcnt(12)
	v_mfma_f32_16x16x32_bf16 v[40:43], v[122:125], v[102:105], v[40:43]
	v_mfma_f32_16x16x32_bf16 v[4:7], v[122:125], v[106:109], v[4:7]
	s_waitcnt lgkmcnt(11)
	v_mfma_f32_16x16x32_bf16 v[0:3], v[126:129], v[106:109], v[0:3]
	v_mfma_f32_16x16x32_bf16 v[36:39], v[126:129], v[102:105], v[36:39]
	s_waitcnt lgkmcnt(10)
	v_mfma_f32_16x16x32_bf16 v[32:35], v[130:133], v[102:105], v[32:35]
	v_mfma_f32_16x16x32_bf16 v[16:19], v[130:133], v[106:109], v[16:19]
	s_waitcnt lgkmcnt(8)
	v_mfma_f32_16x16x32_bf16 v[60:63], v[166:169], v[174:177], v[60:63]
	s_waitcnt lgkmcnt(7)
	v_mfma_f32_16x16x32_bf16 v[56:59], v[170:173], v[174:177], v[56:59]
	s_waitcnt lgkmcnt(6)
	v_mfma_f32_16x16x32_bf16 v[28:31], v[166:169], v[178:181], v[28:31]
	v_mfma_f32_16x16x32_bf16 v[24:27], v[170:173], v[178:181], v[24:27]
	s_waitcnt lgkmcnt(5)
	v_mfma_f32_16x16x32_bf16 v[20:23], v[182:185], v[178:181], v[20:23]
	v_mfma_f32_16x16x32_bf16 v[52:55], v[182:185], v[174:177], v[52:55]
	s_waitcnt lgkmcnt(4)
	v_mfma_f32_16x16x32_bf16 v[48:51], v[186:189], v[174:177], v[48:51]
	v_mfma_f32_16x16x32_bf16 v[12:15], v[186:189], v[178:181], v[12:15]
	s_waitcnt lgkmcnt(3)
	v_mfma_f32_16x16x32_bf16 v[8:11], v[190:193], v[178:181], v[8:11]
	v_mfma_f32_16x16x32_bf16 v[44:47], v[190:193], v[174:177], v[44:47]
	s_waitcnt lgkmcnt(2)
	v_mfma_f32_16x16x32_bf16 v[40:43], v[194:197], v[174:177], v[40:43]
	v_mfma_f32_16x16x32_bf16 v[4:7], v[194:197], v[178:181], v[4:7]
	s_waitcnt lgkmcnt(1)
	v_mfma_f32_16x16x32_bf16 v[0:3], v[198:201], v[178:181], v[0:3]
	v_mfma_f32_16x16x32_bf16 v[36:39], v[198:201], v[174:177], v[36:39]
	s_waitcnt lgkmcnt(0)
	v_mfma_f32_16x16x32_bf16 v[32:35], v[202:205], v[174:177], v[32:35]
	v_mfma_f32_16x16x32_bf16 v[16:19], v[202:205], v[178:181], v[16:19]
	s_cbranch_scc0 .LBB0_1759
	v_add_u32_e32 v138, s35, v80
	v_add_u32_e32 v126, v138, v81
	s_waitcnt vmcnt(0)
	s_barrier
	ds_read_b128 v[74:77], v126 offset:16384
	v_add3_u32 v102, s35, v81, v82
	ds_read_b128 v[94:97], v102
	ds_read_b128 v[98:101], v126 offset:18432
	ds_read_b128 v[102:105], v102 offset:2048
	ds_read_b128 v[106:109], v126 offset:20480
	ds_read_b128 v[110:113], v126 offset:22528
	ds_read_b128 v[114:117], v126 offset:24576
	ds_read_b128 v[118:121], v126 offset:26624
	v_add3_u32 v134, s35, v83, v82
	v_add_u32_e32 v142, v138, v83
	ds_read_b128 v[122:125], v126 offset:28672
	ds_read_b128 v[126:129], v126 offset:30720
	ds_read_b128 v[130:133], v134
	ds_read_b128 v[134:137], v134 offset:2048
	ds_read_b128 v[138:141], v142 offset:16384
	ds_read_b128 v[146:149], v142 offset:18432
	s_waitcnt lgkmcnt(11)
	v_mfma_f32_16x16x32_bf16 v[56:59], v[98:101], v[94:97], v[56:59]
	s_lshl_b32 s33, s33, 7
	s_lshl_b32 s26, s31, 7
	s_ashr_i32 s27, s26, 31
	v_mfma_f32_16x16x32_bf16 v[60:63], v[74:77], v[94:97], v[60:63]
	s_lshl_b64 s[26:27], s[26:27], 1
	s_add_i32 s30, s30, s28
	s_cmpk_gt_i32 s30, 0xfff
	s_waitcnt lgkmcnt(0)
	v_mfma_f32_16x16x32_bf16 v[56:59], v[146:149], v[130:133], v[56:59]
	v_mfma_f32_16x16x32_bf16 v[48:51], v[110:113], v[94:97], v[48:51]
	v_mfma_f32_16x16x32_bf16 v[52:55], v[106:109], v[94:97], v[52:55]
	s_nop 5
	v_max_f32_e32 v56, v56, v56
	v_max_f32_e32 v57, v57, v57
	v_max_f32_e32 v56, 0, v56
	v_mfma_f32_16x16x32_bf16 v[44:47], v[114:117], v[94:97], v[44:47]
	v_max_f32_e32 v57, 0, v57
	v_max_f32_e32 v59, v59, v59
	v_max_f32_e32 v59, 0, v59
	v_mfma_f32_16x16x32_bf16 v[40:43], v[118:121], v[94:97], v[40:43]
	v_mfma_f32_16x16x32_bf16 v[36:39], v[122:125], v[94:97], v[36:39]
	v_mfma_f32_16x16x32_bf16 v[32:35], v[126:129], v[94:97], v[32:35]
	ds_read_b128 v[94:97], v142 offset:20480
	ds_read_b128 v[150:153], v142 offset:22528
	ds_read_b128 v[154:157], v142 offset:24576
	ds_read_b128 v[158:161], v142 offset:26624
	v_mfma_f32_16x16x32_bf16 v[60:63], v[138:141], v[130:133], v[60:63]
	s_waitcnt lgkmcnt(2)
	v_mfma_f32_16x16x32_bf16 v[48:51], v[150:153], v[130:133], v[48:51]
	v_mfma_f32_16x16x32_bf16 v[20:23], v[106:109], v[102:105], v[20:23]
	v_mul_f32_e64 v106, v56, v56
	v_mul_f32_e64 v107, v57, v57
	v_max_f32_e32 v57, v58, v58
	s_nop 1
	v_max_f32_e32 v60, v60, v60
	v_mfma_f32_16x16x32_bf16 v[24:27], v[98:101], v[102:105], v[24:27]
	v_add_u32_e32 v100, s33, v79
	v_mov_b64_e32 v[98:99], s[0:1]
	v_max_f32_e32 v61, v61, v61
	v_max_f32_e32 v56, v62, v62
	v_max_f32_e32 v58, 0, v57
	v_max_f32_e32 v57, v63, v63
	v_mad_i64_i32 v[100:101], s[34:35], v100, s29, v[98:99]
	v_max_f32_e32 v60, 0, v60
	v_max_f32_e32 v61, 0, v61
	v_max_f32_e32 v56, 0, v56
	v_max_f32_e32 v57, 0, v57
	v_mfma_f32_16x16x32_bf16 v[52:55], v[94:97], v[130:133], v[52:55]
	v_lshl_add_u64 v[100:101], v[100:101], 0, s[26:27]
	v_pk_mul_f32 v[60:61], v[60:61], v[60:61]
	v_pk_mul_f32 v[62:63], v[56:57], v[56:57]
	v_mfma_f32_16x16x32_bf16 v[28:31], v[74:77], v[102:105], v[28:31]
	v_max_f32_e32 v48, v48, v48
	v_max_f32_e32 v49, v49, v49
	ds_read_b128 v[74:77], v142 offset:28672
	ds_read_b128 v[162:165], v142 offset:30720
	v_mfma_f32_16x16x32_bf16 v[12:15], v[110:113], v[102:105], v[12:15]
	v_lshl_add_u64 v[100:101], v[100:101], 0, v[64:65]
	v_cvt_pk_bf16_f32 v56, v60, v61
	v_cvt_pk_bf16_f32 v57, v62, v63
	v_mfma_f32_16x16x32_bf16 v[8:11], v[114:117], v[102:105], v[8:11]
	v_max_f32_e32 v48, 0, v48
	v_max_f32_e32 v49, 0, v49
	v_max_f32_e32 v52, v52, v52
	v_mfma_f32_16x16x32_bf16 v[4:7], v[118:121], v[102:105], v[4:7]
	v_max_f32_e32 v53, v53, v53
	v_max_f32_e32 v51, v51, v51
	v_max_f32_e32 v52, 0, v52
	v_mfma_f32_16x16x32_bf16 v[0:3], v[122:125], v[102:105], v[0:3]
	v_max_f32_e32 v53, 0, v53
	v_max_f32_e32 v51, 0, v51
	v_pk_mul_f32 v[52:53], v[52:53], v[52:53]
	v_mfma_f32_16x16x32_bf16 v[16:19], v[126:129], v[102:105], v[16:19]
	v_mul_f32_e64 v102, v58, v58
	v_mul_f32_e64 v103, v59, v59
	v_cvt_pk_bf16_f32 v58, v106, v107
	v_cvt_pk_bf16_f32 v59, v102, v103
	s_waitcnt lgkmcnt(2)
	v_mfma_f32_16x16x32_bf16 v[40:43], v[158:161], v[130:133], v[40:43]
	global_store_dwordx4 v[100:101], v[56:59], off
	s_nop 1
	v_pk_mul_f32 v[56:57], v[48:49], v[48:49]
	v_max_f32_e32 v49, v50, v50
	v_max_f32_e32 v48, v54, v54
	v_max_f32_e32 v50, 0, v49
	v_max_f32_e32 v49, v55, v55
	v_mfma_f32_16x16x32_bf16 v[44:47], v[154:157], v[130:133], v[44:47]
	v_max_f32_e32 v48, 0, v48
	v_max_f32_e32 v49, 0, v49
	v_pk_mul_f32 v[54:55], v[48:49], v[48:49]
	v_pk_mul_f32 v[58:59], v[50:51], v[50:51]
	v_max_f32_e32 v40, v40, v40
	v_max_f32_e32 v41, v41, v41
	s_waitcnt lgkmcnt(0)
	v_mfma_f32_16x16x32_bf16 v[32:35], v[162:165], v[130:133], v[32:35]
	v_cvt_pk_bf16_f32 v48, v52, v53
	v_cvt_pk_bf16_f32 v49, v54, v55
	v_cvt_pk_bf16_f32 v50, v56, v57
	v_cvt_pk_bf16_f32 v51, v58, v59
	v_max_f32_e32 v40, 0, v40
	v_max_f32_e32 v41, 0, v41
	global_store_dwordx4 v[100:101], v[48:51], off offset:64
	v_max_f32_e32 v44, v44, v44
	v_max_f32_e32 v45, v45, v45
	v_pk_mul_f32 v[48:49], v[40:41], v[40:41]
	v_max_f32_e32 v41, v42, v42
	v_max_f32_e32 v40, v46, v46
	v_max_f32_e32 v42, 0, v41
	v_max_f32_e32 v41, v47, v47
	v_max_f32_e32 v43, v43, v43
	v_mfma_f32_16x16x32_bf16 v[36:39], v[74:77], v[130:133], v[36:39]
	v_max_f32_e32 v44, 0, v44
	v_max_f32_e32 v45, 0, v45
	v_max_f32_e32 v40, 0, v40
	v_max_f32_e32 v41, 0, v41
	v_max_f32_e32 v43, 0, v43
	v_pk_mul_f32 v[44:45], v[44:45], v[44:45]
	v_pk_mul_f32 v[46:47], v[40:41], v[40:41]
	v_pk_mul_f32 v[50:51], v[42:43], v[42:43]
	v_max_f32_e32 v32, v32, v32
	v_max_f32_e32 v33, v33, v33
	v_mfma_f32_16x16x32_bf16 v[24:27], v[146:149], v[134:137], v[24:27]
	v_cvt_pk_bf16_f32 v40, v44, v45
	v_cvt_pk_bf16_f32 v41, v46, v47
	v_cvt_pk_bf16_f32 v42, v48, v49
	v_cvt_pk_bf16_f32 v43, v50, v51
	v_max_f32_e32 v32, 0, v32
	v_max_f32_e32 v33, 0, v33
	global_store_dwordx4 v[100:101], v[40:43], off offset:128
	v_max_f32_e32 v36, v36, v36
	v_max_f32_e32 v37, v37, v37
	v_pk_mul_f32 v[40:41], v[32:33], v[32:33]
	v_max_f32_e32 v33, v34, v34
	v_max_f32_e32 v32, v38, v38
	v_max_f32_e32 v34, 0, v33
	v_max_f32_e32 v33, v39, v39
	v_max_f32_e32 v35, v35, v35
	v_mfma_f32_16x16x32_bf16 v[28:31], v[138:141], v[134:137], v[28:31]
	v_max_f32_e32 v36, 0, v36
	v_max_f32_e32 v37, 0, v37
	v_max_f32_e32 v32, 0, v32
	v_max_f32_e32 v33, 0, v33
	v_max_f32_e32 v35, 0, v35
	v_pk_mul_f32 v[36:37], v[36:37], v[36:37]
	v_pk_mul_f32 v[38:39], v[32:33], v[32:33]
	v_pk_mul_f32 v[42:43], v[34:35], v[34:35]
	v_max_f32_e32 v24, v24, v24
	v_max_f32_e32 v25, v25, v25
	v_mfma_f32_16x16x32_bf16 v[12:15], v[150:153], v[134:137], v[12:15]
	v_cvt_pk_bf16_f32 v32, v36, v37
	v_cvt_pk_bf16_f32 v33, v38, v39
	v_cvt_pk_bf16_f32 v34, v40, v41
	v_cvt_pk_bf16_f32 v35, v42, v43
	v_max_f32_e32 v24, 0, v24
	v_max_f32_e32 v25, 0, v25
	global_store_dwordx4 v[100:101], v[32:35], off offset:192
	v_max_f32_e32 v28, v28, v28
	v_max_f32_e32 v29, v29, v29
	v_pk_mul_f32 v[34:35], v[24:25], v[24:25]
	v_max_f32_e32 v25, v26, v26
	v_add_u32_e32 v32, s33, v84
	v_max_f32_e32 v24, v30, v30
	v_max_f32_e32 v26, 0, v25
	v_max_f32_e32 v25, v31, v31
	v_max_f32_e32 v27, v27, v27
	v_mfma_f32_16x16x32_bf16 v[20:23], v[94:97], v[134:137], v[20:23]
	v_mad_i64_i32 v[32:33], s[34:35], v32, s29, v[98:99]
	v_max_f32_e32 v28, 0, v28
	v_max_f32_e32 v29, 0, v29
	v_max_f32_e32 v24, 0, v24
	v_max_f32_e32 v25, 0, v25
	v_max_f32_e32 v27, 0, v27
	v_lshl_add_u64 v[32:33], v[32:33], 0, s[26:27]
	v_pk_mul_f32 v[28:29], v[28:29], v[28:29]
	v_pk_mul_f32 v[30:31], v[24:25], v[24:25]
	v_pk_mul_f32 v[36:37], v[26:27], v[26:27]
	v_max_f32_e32 v12, v12, v12
	v_max_f32_e32 v13, v13, v13
	v_mfma_f32_16x16x32_bf16 v[4:7], v[158:161], v[134:137], v[4:7]
	v_lshl_add_u64 v[32:33], v[32:33], 0, v[64:65]
	v_cvt_pk_bf16_f32 v24, v28, v29
	v_cvt_pk_bf16_f32 v25, v30, v31
	v_cvt_pk_bf16_f32 v26, v34, v35
	v_cvt_pk_bf16_f32 v27, v36, v37
	v_max_f32_e32 v12, 0, v12
	v_max_f32_e32 v13, 0, v13
	global_store_dwordx4 v[32:33], v[24:27], off
	v_max_f32_e32 v20, v20, v20
	v_max_f32_e32 v21, v21, v21
	v_pk_mul_f32 v[24:25], v[12:13], v[12:13]
	v_max_f32_e32 v13, v14, v14
	v_max_f32_e32 v12, v22, v22
	v_max_f32_e32 v14, 0, v13
	v_max_f32_e32 v13, v23, v23
	v_max_f32_e32 v15, v15, v15
	v_mfma_f32_16x16x32_bf16 v[8:11], v[154:157], v[134:137], v[8:11]
	v_max_f32_e32 v20, 0, v20
	v_max_f32_e32 v21, 0, v21
	v_max_f32_e32 v12, 0, v12
	v_max_f32_e32 v13, 0, v13
	v_max_f32_e32 v15, 0, v15
	v_pk_mul_f32 v[20:21], v[20:21], v[20:21]
	v_pk_mul_f32 v[22:23], v[12:13], v[12:13]
	v_pk_mul_f32 v[26:27], v[14:15], v[14:15]
	v_max_f32_e32 v4, v4, v4
	v_max_f32_e32 v5, v5, v5
	v_cvt_pk_bf16_f32 v12, v20, v21
	v_cvt_pk_bf16_f32 v13, v22, v23
	v_cvt_pk_bf16_f32 v14, v24, v25
	v_cvt_pk_bf16_f32 v15, v26, v27
	v_max_f32_e32 v4, 0, v4
	v_max_f32_e32 v5, 0, v5
	global_store_dwordx4 v[32:33], v[12:15], off offset:64
	v_mfma_f32_16x16x32_bf16 v[0:3], v[74:77], v[134:137], v[0:3]
	v_max_f32_e32 v8, v8, v8
	v_pk_mul_f32 v[12:13], v[4:5], v[4:5]
	v_max_f32_e32 v5, v6, v6
	v_mfma_f32_16x16x32_bf16 v[16:19], v[162:165], v[134:137], v[16:19]
	v_max_f32_e32 v9, v9, v9
	v_max_f32_e32 v4, v10, v10
	v_max_f32_e32 v6, 0, v5
	v_max_f32_e32 v5, v11, v11
	v_max_f32_e32 v7, v7, v7
	v_max_f32_e32 v8, 0, v8
	v_max_f32_e32 v9, 0, v9
	v_max_f32_e32 v4, 0, v4
	v_max_f32_e32 v5, 0, v5
	v_max_f32_e32 v7, 0, v7
	v_pk_mul_f32 v[8:9], v[8:9], v[8:9]
	v_pk_mul_f32 v[10:11], v[4:5], v[4:5]
	v_pk_mul_f32 v[14:15], v[6:7], v[6:7]
	v_cvt_pk_bf16_f32 v4, v8, v9
	v_cvt_pk_bf16_f32 v5, v10, v11
	v_cvt_pk_bf16_f32 v6, v12, v13
	v_cvt_pk_bf16_f32 v7, v14, v15
	global_store_dwordx4 v[32:33], v[4:7], off offset:128
	v_max_f32_e32 v0, v0, v0
	v_max_f32_e32 v1, v1, v1
	v_max_f32_e32 v4, v16, v16
	v_max_f32_e32 v5, v17, v17
	v_max_f32_e32 v2, v2, v2
	v_max_f32_e32 v6, v18, v18
	v_max_f32_e32 v3, v3, v3
	v_max_f32_e32 v7, v19, v19
	v_max_f32_e32 v0, 0, v0
	v_max_f32_e32 v4, 0, v4
	v_max_f32_e32 v1, 0, v1
	v_max_f32_e32 v5, 0, v5
	v_max_f32_e32 v2, 0, v2
	v_max_f32_e32 v6, 0, v6
	v_max_f32_e32 v3, 0, v3
	v_max_f32_e32 v7, 0, v7
	v_pk_mul_f32 v[0:1], v[0:1], v[0:1]
	v_pk_mul_f32 v[4:5], v[4:5], v[4:5]
	v_pk_mul_f32 v[2:3], v[2:3], v[2:3]
	v_pk_mul_f32 v[6:7], v[6:7], v[6:7]
	v_cvt_pk_bf16_f32 v0, v0, v1
	v_cvt_pk_bf16_f32 v1, v2, v3
	v_cvt_pk_bf16_f32 v2, v4, v5
	v_cvt_pk_bf16_f32 v3, v6, v7
	global_store_dwordx4 v[32:33], v[0:3], off offset:192
	s_cbranch_scc0 .LBB0_1754

.LBB0_1824:
	s_add_i32 s41, s39, 0x8000
	s_and_b32 s40, s41, 0x8000
	s_add_i32 s40, s40, 0
	s_add_u32 s86, s40, s87
	s_mov_b32 m0, s86
	s_waitcnt vmcnt(0) lgkmcnt(0)
	s_barrier
	global_load_lds_dwordx4 v244, s[96:97]
	s_add_u32 m0, s86, 0x4000
	s_nop 0
	global_load_lds_dwordx4 v245, s[88:89]
	s_add_u32 m0, s86, 0x1000
	s_nop 0
	global_load_lds_dwordx4 v246, s[96:97]
	s_add_u32 m0, s86, 0x5000
	s_nop 0
	global_load_lds_dwordx4 v247, s[88:89]
	s_add_u32 m0, s86, 0x2000
	s_nop 0
	global_load_lds_dwordx4 v248, s[96:97]
	s_add_u32 m0, s86, 0x6000
	s_nop 0
	global_load_lds_dwordx4 v249, s[88:89]
	s_add_u32 m0, s86, 0x3000
	s_nop 0
	global_load_lds_dwordx4 v250, s[96:97]
	s_add_u32 m0, s86, 0x7000
	s_nop 0
	global_load_lds_dwordx4 v251, s[88:89]
	s_add_u32 s96, s96, 0x80
	s_addc_u32 s97, s97, 0
	s_add_u32 s88, s88, 0x80
	s_addc_u32 s89, s89, 0
	s_and_b32 s39, s39, 0x8000
	s_add_i32 s39, s39, 0
	v_add3_u32 v145, s39, v84, v85
	v_add3_u32 v178, s39, v85, v86
	v_add3_u32 v179, s39, v84, v87
	v_add3_u32 v180, s39, v86, v87
	ds_read_b128 v[104:107], v178
	ds_read_b128 v[76:79], v145 offset:16384
	ds_read_b128 v[100:103], v145 offset:18432
	ds_read_b128 v[108:111], v178 offset:2048
	ds_read_b128 v[112:115], v145 offset:20480
	ds_read_b128 v[116:119], v145 offset:22528
	ds_read_b128 v[120:123], v145 offset:24576
	ds_read_b128 v[124:127], v145 offset:26624
	ds_read_b128 v[128:131], v145 offset:28672
	ds_read_b128 v[132:135], v145 offset:30720
	ds_read_b128 v[146:149], v180
	ds_read_b128 v[136:139], v179 offset:16384
	ds_read_b128 v[140:143], v179 offset:18432
	ds_read_b128 v[150:153], v180 offset:2048
	ds_read_b128 v[154:157], v179 offset:20480
	ds_read_b128 v[158:161], v179 offset:22528
	ds_read_b128 v[162:165], v179 offset:24576
	ds_read_b128 v[166:169], v179 offset:26624
	ds_read_b128 v[170:173], v179 offset:28672
	ds_read_b128 v[174:177], v179 offset:30720
	s_add_u32 s28, s28, 0x80
	s_addc_u32 s29, s29, 0
	s_cmpk_eq_i32 s28, 0x1f80
	s_mov_b32 s39, s41
	s_waitcnt lgkmcnt(15)
	v_mfma_f32_16x16x32_bf16 v[60:63], v[76:79], v[104:107], v[60:63]
	v_mfma_f32_16x16x32_bf16 v[56:59], v[100:103], v[104:107], v[56:59]
	v_mfma_f32_16x16x32_bf16 v[24:27], v[76:79], v[108:111], v[24:27]
	v_mfma_f32_16x16x32_bf16 v[20:23], v[100:103], v[108:111], v[20:23]
	v_mfma_f32_16x16x32_bf16 v[16:19], v[112:115], v[108:111], v[16:19]
	v_mfma_f32_16x16x32_bf16 v[52:55], v[112:115], v[104:107], v[52:55]
	s_waitcnt lgkmcnt(14)
	v_mfma_f32_16x16x32_bf16 v[48:51], v[116:119], v[104:107], v[48:51]
	v_mfma_f32_16x16x32_bf16 v[12:15], v[116:119], v[108:111], v[12:15]
	s_waitcnt lgkmcnt(13)
	v_mfma_f32_16x16x32_bf16 v[8:11], v[120:123], v[108:111], v[8:11]
	v_mfma_f32_16x16x32_bf16 v[44:47], v[120:123], v[104:107], v[44:47]
	s_waitcnt lgkmcnt(12)
	v_mfma_f32_16x16x32_bf16 v[40:43], v[124:127], v[104:107], v[40:43]
	v_mfma_f32_16x16x32_bf16 v[4:7], v[124:127], v[108:111], v[4:7]
	s_waitcnt lgkmcnt(11)
	v_mfma_f32_16x16x32_bf16 v[0:3], v[128:131], v[108:111], v[0:3]
	v_mfma_f32_16x16x32_bf16 v[32:35], v[128:131], v[104:107], v[32:35]
	s_waitcnt lgkmcnt(10)
	v_mfma_f32_16x16x32_bf16 v[28:31], v[132:135], v[104:107], v[28:31]
	v_mfma_f32_16x16x32_bf16 v[36:39], v[132:135], v[108:111], v[36:39]
	s_waitcnt lgkmcnt(8)
	v_mfma_f32_16x16x32_bf16 v[60:63], v[136:139], v[146:149], v[60:63]
	s_waitcnt lgkmcnt(7)
	v_mfma_f32_16x16x32_bf16 v[56:59], v[140:143], v[146:149], v[56:59]
	s_waitcnt lgkmcnt(6)
	v_mfma_f32_16x16x32_bf16 v[24:27], v[136:139], v[150:153], v[24:27]
	v_mfma_f32_16x16x32_bf16 v[20:23], v[140:143], v[150:153], v[20:23]
	s_waitcnt lgkmcnt(5)
	v_mfma_f32_16x16x32_bf16 v[16:19], v[154:157], v[150:153], v[16:19]
	v_mfma_f32_16x16x32_bf16 v[52:55], v[154:157], v[146:149], v[52:55]
	s_waitcnt lgkmcnt(4)
	v_mfma_f32_16x16x32_bf16 v[48:51], v[158:161], v[146:149], v[48:51]
	v_mfma_f32_16x16x32_bf16 v[12:15], v[158:161], v[150:153], v[12:15]
	s_waitcnt lgkmcnt(3)
	v_mfma_f32_16x16x32_bf16 v[8:11], v[162:165], v[150:153], v[8:11]
	v_mfma_f32_16x16x32_bf16 v[44:47], v[162:165], v[146:149], v[44:47]
	s_waitcnt lgkmcnt(2)
	v_mfma_f32_16x16x32_bf16 v[40:43], v[166:169], v[146:149], v[40:43]
	v_mfma_f32_16x16x32_bf16 v[4:7], v[166:169], v[150:153], v[4:7]
	s_waitcnt lgkmcnt(1)
	v_mfma_f32_16x16x32_bf16 v[0:3], v[170:173], v[150:153], v[0:3]
	v_mfma_f32_16x16x32_bf16 v[32:35], v[170:173], v[146:149], v[32:35]
	s_waitcnt lgkmcnt(0)
	v_mfma_f32_16x16x32_bf16 v[28:31], v[174:177], v[146:149], v[28:31]
	v_mfma_f32_16x16x32_bf16 v[36:39], v[174:177], v[150:153], v[36:39]
	s_cbranch_scc0 .LBB0_1824
	v_add_u32_e32 v80, s40, v84
	v_add_u32_e32 v81, v80, v85
	s_waitcnt vmcnt(0)
	s_barrier
	ds_read_b128 v[72:75], v81 offset:16384
	v_add3_u32 v99, s40, v85, v86
	ds_read_b128 v[76:79], v81 offset:18432
	ds_read_b128 v[100:103], v99
	ds_read_b128 v[104:107], v99 offset:2048
	ds_read_b128 v[108:111], v81 offset:20480
	ds_read_b128 v[112:115], v81 offset:22528
	ds_read_b128 v[116:119], v81 offset:24576
	ds_read_b128 v[120:123], v81 offset:26624
	ds_read_b128 v[124:127], v81 offset:28672
	ds_read_b128 v[128:131], v81 offset:30720
	v_add_u32_e32 v80, v80, v87
	s_waitcnt lgkmcnt(7)
	v_mfma_f32_16x16x32_bf16 v[60:63], v[72:75], v[100:103], v[60:63]
	s_lshl_b32 s38, s38, 7
	v_mfma_f32_16x16x32_bf16 v[56:59], v[76:79], v[100:103], v[56:59]
	s_waitcnt lgkmcnt(4)
	v_mfma_f32_16x16x32_bf16 v[48:51], v[112:115], v[100:103], v[48:51]
	s_waitcnt lgkmcnt(3)
	v_mfma_f32_16x16x32_bf16 v[44:47], v[116:119], v[100:103], v[44:47]
	s_waitcnt lgkmcnt(2)
	v_mfma_f32_16x16x32_bf16 v[40:43], v[120:123], v[100:103], v[40:43]
	s_waitcnt lgkmcnt(1)
	v_mfma_f32_16x16x32_bf16 v[32:35], v[124:127], v[100:103], v[32:35]
	s_waitcnt lgkmcnt(0)
	v_mfma_f32_16x16x32_bf16 v[28:31], v[128:131], v[100:103], v[28:31]
	v_mfma_f32_16x16x32_bf16 v[24:27], v[72:75], v[104:107], v[24:27]
	ds_read_b128 v[72:75], v80 offset:16384
	v_mfma_f32_16x16x32_bf16 v[52:55], v[108:111], v[100:103], v[52:55]
	v_mfma_f32_16x16x32_bf16 v[20:23], v[76:79], v[104:107], v[20:23]
	v_mfma_f32_16x16x32_bf16 v[16:19], v[108:111], v[104:107], v[16:19]
	v_mfma_f32_16x16x32_bf16 v[12:15], v[112:115], v[104:107], v[12:15]
	v_mfma_f32_16x16x32_bf16 v[8:11], v[116:119], v[104:107], v[8:11]
	v_mfma_f32_16x16x32_bf16 v[4:7], v[120:123], v[104:107], v[4:7]
	v_mfma_f32_16x16x32_bf16 v[0:3], v[124:127], v[104:107], v[0:3]
	v_mfma_f32_16x16x32_bf16 v[100:103], v[128:131], v[104:107], v[36:39]
	s_nop 2
	v_add3_u32 v36, s40, v87, v86
	ds_read_b128 v[76:79], v80 offset:18432
	ds_read_b128 v[104:107], v36
	ds_read_b128 v[108:111], v36 offset:2048
	ds_read_b128 v[128:131], v80 offset:28672
	ds_read_b128 v[132:135], v80 offset:30720
	ds_read_b128 v[112:115], v80 offset:20480
	ds_read_b128 v[116:119], v80 offset:22528
	ds_read_b128 v[120:123], v80 offset:24576
	ds_read_b128 v[124:127], v80 offset:26624
	s_waitcnt lgkmcnt(7)
	v_mfma_f32_16x16x32_bf16 v[60:63], v[72:75], v[104:107], v[60:63]
	s_waitcnt lgkmcnt(5)
	v_mfma_f32_16x16x32_bf16 v[36:39], v[128:131], v[104:107], v[32:35]
	s_waitcnt lgkmcnt(4)
	v_mfma_f32_16x16x32_bf16 v[32:35], v[132:135], v[104:107], v[28:31]
	v_mfma_f32_16x16x32_bf16 v[28:31], v[72:75], v[108:111], v[24:27]
	v_add_u32_e32 v72, s38, v83
	v_mul_hi_i32 v73, v72, s31
	v_mfma_f32_16x16x32_bf16 v[24:27], v[76:79], v[108:111], v[20:23]
	s_waitcnt lgkmcnt(3)
	v_mfma_f32_16x16x32_bf16 v[20:23], v[112:115], v[108:111], v[16:19]
	s_waitcnt lgkmcnt(2)
	v_mfma_f32_16x16x32_bf16 v[16:19], v[116:119], v[108:111], v[12:15]
	s_waitcnt lgkmcnt(1)
	v_mfma_f32_16x16x32_bf16 v[12:15], v[120:123], v[108:111], v[8:11]
	s_waitcnt lgkmcnt(0)
	v_mfma_f32_16x16x32_bf16 v[8:11], v[124:127], v[108:111], v[4:7]
	s_nop 2
	v_lshrrev_b32_e32 v4, 31, v73
	v_ashrrev_i32_e32 v5, 11, v73
	v_mfma_f32_16x16x32_bf16 v[56:59], v[76:79], v[104:107], v[56:59]
	v_add_u32_e32 v73, v5, v4
	v_mad_i32_i24 v78, v73, s33, v72
	v_lshlrev_b32_e32 v75, 13, v73
	v_mfma_f32_16x16x32_bf16 v[52:55], v[112:115], v[104:107], v[52:55]
	v_cmp_lt_i32_e32 vcc, s34, v78
	v_add3_u32 v74, v75, v78, s35
	v_mfma_f32_16x16x32_bf16 v[48:51], v[116:119], v[104:107], v[48:51]
	v_mfma_f32_16x16x32_bf16 v[44:47], v[120:123], v[104:107], v[44:47]
	v_mfma_f32_16x16x32_bf16 v[40:43], v[124:127], v[104:107], v[40:43]
	v_mfma_f32_16x16x32_bf16 v[4:7], v[128:131], v[108:111], v[0:3]
	v_mfma_f32_16x16x32_bf16 v[0:3], v[132:135], v[108:111], v[100:103]
	s_and_saveexec_b64 s[28:29], vcc
	s_xor_b64 s[28:29], exec, s[28:29]
	v_add3_u32 v72, v75, v78, s35
	s_or_saveexec_b64 s[28:29], s[28:29]
	v_mov_b64_e32 v[76:77], s[92:93]
	v_lshl_add_u32 v75, v73, 8, v78
	s_xor_b64 exec, exec, s[28:29]
	v_lshl_add_u32 v72, v73, 8, v78
	v_mov_b64_e32 v[76:77], s[2:3]
	s_or_b64 exec, exec, s[28:29]
	s_and_saveexec_b64 s[28:29], vcc
	s_xor_b64 s[28:29], exec, s[28:29]
	s_cbranch_execz .LBB0_1831
	v_add_u32_e32 v73, 3, v73
	v_mul_hi_i32_i24_e32 v79, 0x6000, v73
	v_mul_i32_i24_e32 v78, 0x6000, v73
	s_or_saveexec_b64 s[28:29], s[28:29]
	v_mov_b64_e32 v[80:81], s[92:93]
	s_xor_b64 exec, exec, s[28:29]
	s_cbranch_execnz .LBB0_1832
	s_branch .LBB0_1833
